# GU epilogue: row sum-of-squares loads hoisted to tile start (no vmcnt(0) stalls in swiglu epilogue), on top of v4
# speedup vs baseline: 1.0068x; 1.0012x over previous
.LBB0_399:
	v_lshrrev_b32_e32 v250, 8, v252
	v_lshlrev_b32_e32 v250, 6, v250
	v_and_or_b32 v250, v252, 15, v250
	v_lshl_add_u32 v250, s16, 8, v250
	v_mov_b32_e32 v251, 0
	v_lshl_add_u64 v[248:249], v[250:251], 2, s[6:7]
	global_load_dword v231, v[248:249], off
	global_load_dword v232, v[248:249], off offset:64
	global_load_dword v233, v[248:249], off offset:128
	global_load_dword v234, v[248:249], off offset:192
	global_load_dword v235, v[248:249], off offset:512
	global_load_dword v236, v[248:249], off offset:576
	global_load_dword v237, v[248:249], off offset:640
	global_load_dword v238, v[248:249], off offset:704
	s_mov_b32 s5, s87
	v_readlane_b32 s9, v254, 37
	s_mul_hi_u32 s9, s5, s9
	s_add_i32 s37, s37, 1
	s_mul_i32 s9, s9, s86
	s_mul_i32 s1, s37, s36
	s_mul_hi_u32 s4, s37, s86
	s_sub_i32 s5, s5, s9
	s_add_i32 s4, s4, s1
	s_sub_i32 s9, s5, s86
	s_cmp_ge_u32 s5, s86
	s_cselect_b32 s5, s9, s5
	s_sub_i32 s9, s5, s86
	s_cmp_ge_u32 s5, s86
	s_cselect_b32 s5, s9, s5
	s_mul_i32 s1, s37, s86
	s_ashr_i32 s9, s5, 31
	s_add_u32 s12, s1, s5
	s_addc_u32 s13, s4, s9
	v_mov_b64_e32 v[0:1], 0x57f
	v_cmp_gt_i64_e64 s[4:5], s[12:13], v[0:1]
	s_and_b64 vcc, exec, s[4:5]
	s_cbranch_vccnz .LBB0_401
	s_ashr_i32 s1, s12, 31
	s_lshr_b32 s1, s1, 29
	s_add_i32 s1, s12, s1
	s_ashr_i32 s8, s1, 3
	s_and_b32 s1, s1, -8
	s_sub_i32 s1, s12, s1
	s_lshr_b32 s9, s1, 31
	s_or_b32 s9, s9, 0xb0
	s_mul_i32 s1, s9, s1
	s_add_i32 s1, s1, s8
	s_mul_hi_i32 s8, s1, 0x2e8ba2e9
	s_lshr_b32 s9, s8, 31
	s_ashr_i32 s8, s8, 4
	s_add_i32 s8, s8, s9
	s_lshl_b32 s9, s8, 2
	s_sub_i32 s10, 64, s9
	s_min_i32 s11, s10, 4
	s_abs_i32 s10, s11
	v_cvt_f32_u32_e32 v0, s10
	s_sub_i32 s15, 0, s10
	s_mulk_i32 s8, 0x58
	s_sub_i32 s1, s1, s8
	v_rcp_iflag_f32_e32 v0, v0
	s_abs_i32 s8, s1
	s_xor_b32 s14, s1, s11
	s_ashr_i32 s14, s14, 31
	v_mul_f32_e32 v0, 0x4f7ffffe, v0
	v_cvt_u32_f32_e32 v0, v0
	s_nop 0
	v_readfirstlane_b32 s22, v0
	s_mul_i32 s15, s15, s22
	s_mul_hi_u32 s15, s22, s15
	s_add_i32 s22, s22, s15
	s_mul_hi_u32 s15, s8, s22
	s_mul_i32 s22, s15, s10
	s_sub_i32 s8, s8, s22
	s_add_i32 s23, s15, 1
	s_sub_i32 s22, s8, s10
	s_cmp_ge_u32 s8, s10
	s_cselect_b32 s15, s23, s15
	s_cselect_b32 s8, s22, s8
	s_add_i32 s22, s15, 1
	s_cmp_ge_u32 s8, s10
	s_cselect_b32 s8, s22, s15
	s_xor_b32 s8, s8, s14
	s_sub_i32 s10, s8, s14
	s_mul_i32 s8, s10, s11
	s_sub_i32 s1, s1, s8
	s_add_i32 s8, s1, s9

.LBB0_402:
	s_add_u32 s20, s18, 0xfffc0080
	s_addc_u32 s21, s19, -1
	s_add_i32 s41, 0, 0x10000
	v_add_u32_e32 v142, s41, v145
	ds_read_b128 v[138:141], v142
	ds_read_b128 v[148:151], v142 offset:1024
	ds_read_b128 v[152:155], v142 offset:2048
	ds_read_b128 v[156:159], v142 offset:3072
	s_cmp_eq_u32 s40, 12
	s_cselect_b32 s23, s1, s21
	s_cselect_b32 s22, s9, s20
	s_cselect_b32 s21, s11, s39
	s_cselect_b32 s20, s33, s38
	v_lshl_add_u64 v[142:143], s[18:19], 0, v[136:137]
	s_add_i32 m0, s17, 0xc000
	ds_read_b128 v[160:163], v146
	ds_read_b128 v[164:167], v146 offset:1024
	ds_read_b128 v[168:171], v146 offset:2048
	ds_read_b128 v[172:175], v146 offset:3072
	ds_read_b128 v[176:179], v146 offset:4096
	ds_read_b128 v[180:183], v146 offset:5120
	ds_read_b128 v[184:187], v146 offset:6144
	ds_read_b128 v[188:191], v146 offset:7168
	global_load_lds_dwordx4 v[142:143], off
	v_lshl_add_u64 v[142:143], s[18:19], 0, v[134:135]
	s_add_i32 m0, s17, 0xe000
	s_nop 0
	global_load_lds_dwordx4 v[142:143], off
	s_waitcnt lgkmcnt(8)
	s_barrier
	s_waitcnt lgkmcnt(0)
	s_setprio 1
	s_waitcnt lgkmcnt(0)
	v_mfma_f32_16x16x32_bf16 v[124:127], v[138:141], v[160:163], v[124:127]
	v_mfma_f32_16x16x32_bf16 v[116:119], v[152:155], v[160:163], v[116:119]
	v_mfma_f32_16x16x32_bf16 v[108:111], v[138:141], v[168:171], v[108:111]
	v_mfma_f32_16x16x32_bf16 v[100:103], v[152:155], v[168:171], v[100:103]
	v_mfma_f32_16x16x32_bf16 v[92:95], v[138:141], v[176:179], v[92:95]
	v_mfma_f32_16x16x32_bf16 v[84:87], v[152:155], v[176:179], v[84:87]
	v_mfma_f32_16x16x32_bf16 v[76:79], v[138:141], v[184:187], v[76:79]
	v_mfma_f32_16x16x32_bf16 v[68:71], v[152:155], v[184:187], v[68:71]
	v_mfma_f32_16x16x32_bf16 v[124:127], v[148:151], v[164:167], v[124:127]
	v_mfma_f32_16x16x32_bf16 v[116:119], v[156:159], v[164:167], v[116:119]
	v_mfma_f32_16x16x32_bf16 v[108:111], v[148:151], v[172:175], v[108:111]
	v_mfma_f32_16x16x32_bf16 v[100:103], v[156:159], v[172:175], v[100:103]
	v_mfma_f32_16x16x32_bf16 v[92:95], v[148:151], v[180:183], v[92:95]
	v_mfma_f32_16x16x32_bf16 v[84:87], v[156:159], v[180:183], v[84:87]
	v_mfma_f32_16x16x32_bf16 v[76:79], v[148:151], v[188:191], v[76:79]
	v_mfma_f32_16x16x32_bf16 v[68:71], v[156:159], v[188:191], v[68:71]
	s_setprio 0
	s_barrier
	s_add_i32 s44, 0, 0x14000
	v_add_u32_e32 v142, s44, v145
	s_add_i32 s41, s41, s28
	ds_read_b128 v[198:201], v142
	ds_read_b128 v[206:209], v142 offset:1024
	ds_read_b128 v[210:213], v142 offset:2048
	ds_read_b128 v[214:217], v142 offset:3072
	v_lshl_add_u64 v[142:143], s[20:21], 0, v[192:193]
	s_mov_b32 m0, s41
	v_lshl_add_u64 v[218:219], s[20:21], 0, v[128:129]
	global_load_lds_dwordx4 v[142:143], off
	s_add_i32 m0, s41, 0x2000
	s_nop 0
	global_load_lds_dwordx4 v[218:219], off
	s_barrier
	s_waitcnt lgkmcnt(0)
	s_setprio 1
	s_waitcnt lgkmcnt(0)
	v_mfma_f32_16x16x32_bf16 v[120:123], v[198:201], v[160:163], v[120:123]
	v_mfma_f32_16x16x32_bf16 v[112:115], v[210:213], v[160:163], v[112:115]
	v_mfma_f32_16x16x32_bf16 v[104:107], v[198:201], v[168:171], v[104:107]
	v_mfma_f32_16x16x32_bf16 v[96:99], v[210:213], v[168:171], v[96:99]
	v_mfma_f32_16x16x32_bf16 v[88:91], v[198:201], v[176:179], v[88:91]
	v_mfma_f32_16x16x32_bf16 v[80:83], v[210:213], v[176:179], v[80:83]
	v_mfma_f32_16x16x32_bf16 v[72:75], v[198:201], v[184:187], v[72:75]
	v_mfma_f32_16x16x32_bf16 v[64:67], v[210:213], v[184:187], v[64:67]
	v_mfma_f32_16x16x32_bf16 v[120:123], v[206:209], v[164:167], v[120:123]
	v_mfma_f32_16x16x32_bf16 v[112:115], v[214:217], v[164:167], v[112:115]
	v_mfma_f32_16x16x32_bf16 v[104:107], v[206:209], v[172:175], v[104:107]
	v_mfma_f32_16x16x32_bf16 v[96:99], v[214:217], v[172:175], v[96:99]
	v_mfma_f32_16x16x32_bf16 v[88:91], v[206:209], v[180:183], v[88:91]
	v_mfma_f32_16x16x32_bf16 v[80:83], v[214:217], v[180:183], v[80:83]
	v_mfma_f32_16x16x32_bf16 v[72:75], v[206:209], v[188:191], v[72:75]
	v_mfma_f32_16x16x32_bf16 v[64:67], v[214:217], v[188:191], v[64:67]
	s_setprio 0
	s_mov_b32 m0, s17
	v_lshl_add_u64 v[220:221], s[22:23], 0, v[132:133]
	s_barrier
	ds_read_b128 v[160:163], v146 offset:16384
	ds_read_b128 v[164:167], v146 offset:17408
	ds_read_b128 v[168:171], v146 offset:18432
	ds_read_b128 v[172:175], v146 offset:19456
	ds_read_b128 v[176:179], v146 offset:20480
	ds_read_b128 v[180:183], v146 offset:21504
	ds_read_b128 v[184:187], v146 offset:22528
	ds_read_b128 v[188:191], v146 offset:23552
	global_load_lds_dwordx4 v[220:221], off
	v_lshl_add_u64 v[222:223], s[22:23], 0, v[130:131]
	s_mov_b32 m0, s29
	s_nop 0
	global_load_lds_dwordx4 v[222:223], off
	s_barrier
	s_waitcnt lgkmcnt(0)
	s_setprio 1
	s_waitcnt lgkmcnt(0)
	v_mfma_f32_16x16x32_bf16 v[60:63], v[138:141], v[160:163], v[60:63]
	v_mfma_f32_16x16x32_bf16 v[52:55], v[152:155], v[160:163], v[52:55]
	v_mfma_f32_16x16x32_bf16 v[44:47], v[138:141], v[168:171], v[44:47]
	v_mfma_f32_16x16x32_bf16 v[36:39], v[152:155], v[168:171], v[36:39]
	v_mfma_f32_16x16x32_bf16 v[28:31], v[138:141], v[176:179], v[28:31]
	v_mfma_f32_16x16x32_bf16 v[20:23], v[152:155], v[176:179], v[20:23]
	v_mfma_f32_16x16x32_bf16 v[12:15], v[138:141], v[184:187], v[12:15]
	v_mfma_f32_16x16x32_bf16 v[4:7], v[152:155], v[184:187], v[4:7]
	v_mfma_f32_16x16x32_bf16 v[60:63], v[148:151], v[164:167], v[60:63]
	v_mfma_f32_16x16x32_bf16 v[52:55], v[156:159], v[164:167], v[52:55]
	v_mfma_f32_16x16x32_bf16 v[44:47], v[148:151], v[172:175], v[44:47]
	v_mfma_f32_16x16x32_bf16 v[36:39], v[156:159], v[172:175], v[36:39]
	v_mfma_f32_16x16x32_bf16 v[28:31], v[148:151], v[180:183], v[28:31]
	v_mfma_f32_16x16x32_bf16 v[20:23], v[156:159], v[180:183], v[20:23]
	v_mfma_f32_16x16x32_bf16 v[12:15], v[148:151], v[188:191], v[12:15]
	v_mfma_f32_16x16x32_bf16 v[4:7], v[156:159], v[188:191], v[4:7]
	s_setprio 0
	s_barrier
	s_add_u32 s42, s20, 0x40000
	s_addc_u32 s43, s21, 0
	s_add_i32 s41, s44, s28
	v_lshl_add_u64 v[138:139], s[42:43], 0, v[192:193]
	s_mov_b32 m0, s41
	s_nop 0
	global_load_lds_dwordx4 v[138:139], off
	v_lshl_add_u64 v[138:139], s[42:43], 0, v[128:129]
	s_add_i32 m0, s41, 0x2000
	s_nop 0
	global_load_lds_dwordx4 v[138:139], off
	s_waitcnt vmcnt(6)
	s_barrier
	s_setprio 1
	v_mfma_f32_16x16x32_bf16 v[56:59], v[198:201], v[160:163], v[56:59]
	v_mfma_f32_16x16x32_bf16 v[48:51], v[210:213], v[160:163], v[48:51]
	v_mfma_f32_16x16x32_bf16 v[40:43], v[198:201], v[168:171], v[40:43]
	v_mfma_f32_16x16x32_bf16 v[32:35], v[210:213], v[168:171], v[32:35]
	v_mfma_f32_16x16x32_bf16 v[24:27], v[198:201], v[176:179], v[24:27]
	v_mfma_f32_16x16x32_bf16 v[16:19], v[210:213], v[176:179], v[16:19]
	v_mfma_f32_16x16x32_bf16 v[8:11], v[198:201], v[184:187], v[8:11]
	v_mfma_f32_16x16x32_bf16 v[0:3], v[210:213], v[184:187], v[0:3]
	v_mfma_f32_16x16x32_bf16 v[56:59], v[206:209], v[164:167], v[56:59]
	v_mfma_f32_16x16x32_bf16 v[48:51], v[214:217], v[164:167], v[48:51]
	v_mfma_f32_16x16x32_bf16 v[40:43], v[206:209], v[172:175], v[40:43]
	v_mfma_f32_16x16x32_bf16 v[32:35], v[214:217], v[172:175], v[32:35]
	v_mfma_f32_16x16x32_bf16 v[24:27], v[206:209], v[180:183], v[24:27]
	v_mfma_f32_16x16x32_bf16 v[16:19], v[214:217], v[180:183], v[16:19]
	v_mfma_f32_16x16x32_bf16 v[8:11], v[206:209], v[188:191], v[8:11]
	v_mfma_f32_16x16x32_bf16 v[0:3], v[214:217], v[188:191], v[0:3]
	s_setprio 0
	s_add_i32 s41, 0, 0x18000
	v_add_u32_e32 v144, s41, v145
	s_barrier
	ds_read_b128 v[138:141], v144
	ds_read_b128 v[148:151], v144 offset:1024
	ds_read_b128 v[152:155], v144 offset:2048
	ds_read_b128 v[156:159], v144 offset:3072
	s_add_u32 s22, s22, 0x40000
	s_addc_u32 s23, s23, 0
	s_mov_b32 m0, s30
	v_lshl_add_u64 v[198:199], s[22:23], 0, v[132:133]
	ds_read_b128 v[160:163], v146 offset:32768
	ds_read_b128 v[164:167], v146 offset:33792
	ds_read_b128 v[168:171], v146 offset:34816
	ds_read_b128 v[172:175], v146 offset:35840
	ds_read_b128 v[176:179], v146 offset:36864
	ds_read_b128 v[180:183], v146 offset:37888
	ds_read_b128 v[184:187], v146 offset:38912
	ds_read_b128 v[188:191], v146 offset:39936
	global_load_lds_dwordx4 v[198:199], off
	v_lshl_add_u64 v[198:199], s[22:23], 0, v[130:131]
	s_mov_b32 m0, s31
	s_nop 0
	global_load_lds_dwordx4 v[198:199], off
	s_waitcnt lgkmcnt(8)
	s_barrier
	s_waitcnt lgkmcnt(0)
	s_setprio 1
	s_waitcnt lgkmcnt(0)
	v_mfma_f32_16x16x32_bf16 v[124:127], v[138:141], v[160:163], v[124:127]
	v_mfma_f32_16x16x32_bf16 v[116:119], v[152:155], v[160:163], v[116:119]
	v_mfma_f32_16x16x32_bf16 v[108:111], v[138:141], v[168:171], v[108:111]
	v_mfma_f32_16x16x32_bf16 v[100:103], v[152:155], v[168:171], v[100:103]
	v_mfma_f32_16x16x32_bf16 v[92:95], v[138:141], v[176:179], v[92:95]
	v_mfma_f32_16x16x32_bf16 v[84:87], v[152:155], v[176:179], v[84:87]
	v_mfma_f32_16x16x32_bf16 v[76:79], v[138:141], v[184:187], v[76:79]
	v_mfma_f32_16x16x32_bf16 v[68:71], v[152:155], v[184:187], v[68:71]
	v_mfma_f32_16x16x32_bf16 v[124:127], v[148:151], v[164:167], v[124:127]
	v_mfma_f32_16x16x32_bf16 v[116:119], v[156:159], v[164:167], v[116:119]
	v_mfma_f32_16x16x32_bf16 v[108:111], v[148:151], v[172:175], v[108:111]
	v_mfma_f32_16x16x32_bf16 v[100:103], v[156:159], v[172:175], v[100:103]
	v_mfma_f32_16x16x32_bf16 v[92:95], v[148:151], v[180:183], v[92:95]
	v_mfma_f32_16x16x32_bf16 v[84:87], v[156:159], v[180:183], v[84:87]
	v_mfma_f32_16x16x32_bf16 v[76:79], v[148:151], v[188:191], v[76:79]
	v_mfma_f32_16x16x32_bf16 v[68:71], v[156:159], v[188:191], v[68:71]
	s_setprio 0
	s_barrier
	s_add_i32 s22, 0, 0x1c000
	s_add_i32 s23, s41, s28
	v_add_u32_e32 v144, s22, v145
	v_lshl_add_u64 v[142:143], v[142:143], 0, s[80:81]
	s_mov_b32 m0, s23
	ds_read_b128 v[198:201], v144
	ds_read_b128 v[206:209], v144 offset:1024
	ds_read_b128 v[210:213], v144 offset:2048
	ds_read_b128 v[214:217], v144 offset:3072
	global_load_lds_dwordx4 v[142:143], off
	v_lshl_add_u64 v[142:143], v[218:219], 0, s[80:81]
	s_add_i32 m0, s23, 0x2000
	s_nop 0
	global_load_lds_dwordx4 v[142:143], off
	s_barrier
	s_waitcnt lgkmcnt(0)
	s_setprio 1
	s_waitcnt lgkmcnt(0)
	v_mfma_f32_16x16x32_bf16 v[120:123], v[198:201], v[160:163], v[120:123]
	v_mfma_f32_16x16x32_bf16 v[112:115], v[210:213], v[160:163], v[112:115]
	v_mfma_f32_16x16x32_bf16 v[104:107], v[198:201], v[168:171], v[104:107]
	v_mfma_f32_16x16x32_bf16 v[96:99], v[210:213], v[168:171], v[96:99]
	v_mfma_f32_16x16x32_bf16 v[88:91], v[198:201], v[176:179], v[88:91]
	v_mfma_f32_16x16x32_bf16 v[80:83], v[210:213], v[176:179], v[80:83]
	v_mfma_f32_16x16x32_bf16 v[72:75], v[198:201], v[184:187], v[72:75]
	v_mfma_f32_16x16x32_bf16 v[64:67], v[210:213], v[184:187], v[64:67]
	v_mfma_f32_16x16x32_bf16 v[120:123], v[206:209], v[164:167], v[120:123]
	v_mfma_f32_16x16x32_bf16 v[112:115], v[214:217], v[164:167], v[112:115]
	v_mfma_f32_16x16x32_bf16 v[104:107], v[206:209], v[172:175], v[104:107]
	v_mfma_f32_16x16x32_bf16 v[96:99], v[214:217], v[172:175], v[96:99]
	v_mfma_f32_16x16x32_bf16 v[88:91], v[206:209], v[180:183], v[88:91]
	v_mfma_f32_16x16x32_bf16 v[80:83], v[214:217], v[180:183], v[80:83]
	v_mfma_f32_16x16x32_bf16 v[72:75], v[206:209], v[188:191], v[72:75]
	v_mfma_f32_16x16x32_bf16 v[64:67], v[214:217], v[188:191], v[64:67]
	s_setprio 0
	s_mov_b32 m0, s34
	v_lshl_add_u64 v[142:143], v[220:221], 0, s[80:81]
	s_barrier
	ds_read_b128 v[160:163], v146 offset:49152
	ds_read_b128 v[164:167], v146 offset:50176
	ds_read_b128 v[168:171], v146 offset:51200
	ds_read_b128 v[172:175], v146 offset:52224
	ds_read_b128 v[176:179], v146 offset:53248
	ds_read_b128 v[180:183], v146 offset:54272
	ds_read_b128 v[184:187], v146 offset:55296
	ds_read_b128 v[188:191], v146 offset:56320
	global_load_lds_dwordx4 v[142:143], off
	v_lshl_add_u64 v[142:143], v[222:223], 0, s[80:81]
	s_mov_b32 m0, s35
	s_nop 0
	global_load_lds_dwordx4 v[142:143], off
	s_barrier
	s_waitcnt lgkmcnt(0)
	s_setprio 1
	s_waitcnt lgkmcnt(0)
	v_mfma_f32_16x16x32_bf16 v[60:63], v[138:141], v[160:163], v[60:63]
	v_mfma_f32_16x16x32_bf16 v[52:55], v[152:155], v[160:163], v[52:55]
	v_mfma_f32_16x16x32_bf16 v[44:47], v[138:141], v[168:171], v[44:47]
	v_mfma_f32_16x16x32_bf16 v[36:39], v[152:155], v[168:171], v[36:39]
	v_mfma_f32_16x16x32_bf16 v[28:31], v[138:141], v[176:179], v[28:31]
	v_mfma_f32_16x16x32_bf16 v[20:23], v[152:155], v[176:179], v[20:23]
	v_mfma_f32_16x16x32_bf16 v[12:15], v[138:141], v[184:187], v[12:15]
	v_mfma_f32_16x16x32_bf16 v[4:7], v[152:155], v[184:187], v[4:7]
	v_mfma_f32_16x16x32_bf16 v[60:63], v[148:151], v[164:167], v[60:63]
	v_mfma_f32_16x16x32_bf16 v[52:55], v[156:159], v[164:167], v[52:55]
	v_mfma_f32_16x16x32_bf16 v[44:47], v[148:151], v[172:175], v[44:47]
	v_mfma_f32_16x16x32_bf16 v[36:39], v[156:159], v[172:175], v[36:39]
	v_mfma_f32_16x16x32_bf16 v[28:31], v[148:151], v[180:183], v[28:31]
	v_mfma_f32_16x16x32_bf16 v[20:23], v[156:159], v[180:183], v[20:23]
	v_mfma_f32_16x16x32_bf16 v[12:15], v[148:151], v[188:191], v[12:15]
	v_mfma_f32_16x16x32_bf16 v[4:7], v[156:159], v[188:191], v[4:7]
	s_setprio 0
	s_barrier
	s_add_u32 s20, s20, 0x40080
	s_addc_u32 s21, s21, 0
	s_add_i32 s22, s22, s28
	v_lshl_add_u64 v[138:139], s[20:21], 0, v[192:193]
	s_mov_b32 m0, s22
	s_nop 0
	global_load_lds_dwordx4 v[138:139], off
	v_lshl_add_u64 v[138:139], s[20:21], 0, v[128:129]
	s_add_i32 m0, s22, 0x2000
	s_nop 0
	global_load_lds_dwordx4 v[138:139], off
	s_waitcnt vmcnt(6)
	s_barrier
	s_setprio 1
	v_mfma_f32_16x16x32_bf16 v[56:59], v[198:201], v[160:163], v[56:59]
	v_mfma_f32_16x16x32_bf16 v[48:51], v[210:213], v[160:163], v[48:51]
	v_mfma_f32_16x16x32_bf16 v[40:43], v[198:201], v[168:171], v[40:43]
	v_mfma_f32_16x16x32_bf16 v[32:35], v[210:213], v[168:171], v[32:35]
	v_mfma_f32_16x16x32_bf16 v[24:27], v[198:201], v[176:179], v[24:27]
	v_mfma_f32_16x16x32_bf16 v[16:19], v[210:213], v[176:179], v[16:19]
	v_mfma_f32_16x16x32_bf16 v[8:11], v[198:201], v[184:187], v[8:11]
	v_mfma_f32_16x16x32_bf16 v[0:3], v[210:213], v[184:187], v[0:3]
	v_mfma_f32_16x16x32_bf16 v[56:59], v[206:209], v[164:167], v[56:59]
	v_mfma_f32_16x16x32_bf16 v[48:51], v[214:217], v[164:167], v[48:51]
	v_mfma_f32_16x16x32_bf16 v[40:43], v[206:209], v[172:175], v[40:43]
	v_mfma_f32_16x16x32_bf16 v[32:35], v[214:217], v[172:175], v[32:35]
	v_mfma_f32_16x16x32_bf16 v[24:27], v[206:209], v[180:183], v[24:27]
	v_mfma_f32_16x16x32_bf16 v[16:19], v[214:217], v[180:183], v[16:19]
	v_mfma_f32_16x16x32_bf16 v[8:11], v[206:209], v[188:191], v[8:11]
	v_mfma_f32_16x16x32_bf16 v[0:3], v[214:217], v[188:191], v[0:3]
	s_setprio 0
	s_add_i32 s40, s40, 2
	s_add_u32 s38, s38, 0x100
	s_addc_u32 s39, s39, 0
	s_add_u32 s18, s18, 0x100
	s_addc_u32 s19, s19, 0
	s_cmp_gt_u32 s40, 13
	s_barrier
	s_cbranch_scc0 .LBB0_402
	v_mov_b32_e32 v139, v252
	s_lshl_b32 s9, s16, 8
	v_readfirstlane_b32 s1, v139
	s_ashr_i32 s11, s1, 2
	s_andn2_b32 s11, s11, 63
	s_lshr_b32 s1, s1, 1
	s_add_i32 s11, s11, s9
	s_lshl_b32 s0, s0, 7
	s_and_b32 s1, s1, 0x60
	v_and_or_b32 v138, v139, 15, s11
	s_or_b32 s0, s1, s0
	v_lshrrev_b32_e32 v139, 1, v139
	v_and_or_b32 v142, v139, 24, s0
	v_ashrrev_i32_e32 v139, 31, v138
	v_lshl_add_u64 v[140:141], v[138:139], 2, s[6:7]
	v_pk_mul_f32 v[120:121], v[124:125], v[120:121]
	v_pk_mul_f32 v[122:123], v[126:127], v[122:123]
	v_pk_mul_f32 v[112:113], v[116:117], v[112:113]
	v_pk_mul_f32 v[114:115], v[118:119], v[114:115]
	v_ashrrev_i32_e32 v143, 31, v142
	s_movk_i32 s9, 0x1600
	v_pk_mul_f32 v[104:105], v[108:109], v[104:105]
	v_pk_mul_f32 v[106:107], v[110:111], v[106:107]
	v_pk_mul_f32 v[96:97], v[100:101], v[96:97]
	v_or_b32_e32 v150, 16, v138
	v_pk_mul_f32 v[98:99], v[102:103], v[98:99]
	v_pk_mul_f32 v[88:89], v[92:93], v[88:89]
	v_pk_mul_f32 v[90:91], v[94:95], v[90:91]
	v_pk_mul_f32 v[80:81], v[84:85], v[80:81]
	v_or_b32_e32 v148, 32, v138
	v_pk_mul_f32 v[82:83], v[86:87], v[82:83]
	v_pk_mul_f32 v[72:73], v[76:77], v[72:73]
	v_pk_mul_f32 v[74:75], v[78:79], v[74:75]
	v_pk_mul_f32 v[64:65], v[68:69], v[64:65]
	v_or_b32_e32 v139, 48, v138
	v_pk_mul_f32 v[66:67], v[70:71], v[66:67]
	v_pk_mul_f32 v[56:57], v[60:61], v[56:57]
	v_pk_mul_f32 v[58:59], v[62:63], v[58:59]
	v_pk_mul_f32 v[48:49], v[52:53], v[48:49]
	v_pk_mul_f32 v[50:51], v[54:55], v[50:51]
	v_pk_mul_f32 v[40:41], v[44:45], v[40:41]
	v_pk_mul_f32 v[42:43], v[46:47], v[42:43]
	v_pk_mul_f32 v[32:33], v[36:37], v[32:33]
	v_pk_mul_f32 v[34:35], v[38:39], v[34:35]
	v_pk_mul_f32 v[24:25], v[28:29], v[24:25]
	v_pk_mul_f32 v[26:27], v[30:31], v[26:27]
	v_pk_mul_f32 v[16:17], v[20:21], v[16:17]
	v_pk_mul_f32 v[18:19], v[22:23], v[18:19]
	v_pk_mul_f32 v[8:9], v[12:13], v[8:9]
	v_pk_mul_f32 v[10:11], v[14:15], v[10:11]
	v_pk_mul_f32 v[0:1], v[4:5], v[0:1]
	v_pk_mul_f32 v[2:3], v[6:7], v[2:3]
	s_mov_b32 s16, s8
	s_mov_b64 s[18:19], s[14:15]
	s_mov_b64 s[20:21], s[12:13]
	v_fmamk_f32 v144, v231, 0x3a800000, v194
	v_cmp_gt_f32_e32 vcc, s2, v144
	v_mul_f32_e32 v152, 0x4b800000, v144
	s_nop 0
	v_cndmask_b32_e32 v144, v144, v152, vcc
	v_rsq_f32_e32 v144, v144
	s_nop 0
	v_mul_f32_e32 v152, 0x45800000, v144
	v_cndmask_b32_e32 v144, v144, v152, vcc
	v_mul_f32_e32 v152, 0xbfb8aa3b, v144
	v_pk_mul_f32 v[156:157], v[124:125], v[152:153] op_sel_hi:[1,0]
	v_pk_mul_f32 v[154:155], v[126:127], v[152:153] op_sel_hi:[1,0]
	v_exp_f32_e32 v153, v156
	v_mul_f32_e32 v144, v144, v144
	v_add_f32_e32 v153, 1.0, v153
	v_rcp_f32_e32 v156, v153
	v_exp_f32_e32 v153, v157
	s_nop 0
	v_add_f32_e32 v153, 1.0, v153
	v_rcp_f32_e32 v157, v153
	v_exp_f32_e32 v153, v154
	v_pk_mul_f32 v[124:125], v[144:145], v[156:157] op_sel_hi:[0,1]
	v_add_f32_e32 v153, 1.0, v153
	v_rcp_f32_e32 v154, v153
	v_exp_f32_e32 v153, v155
	v_pk_mul_f32 v[120:121], v[120:121], v[124:125]
	v_add_f32_e32 v153, 1.0, v153
	v_rcp_f32_e32 v155, v153
	v_cvt_pk_bf16_f32 v124, v121, s0
	v_cvt_pk_bf16_f32 v120, v120, s0
	v_readlane_b32 s0, v254, 29
	v_pk_mul_f32 v[126:127], v[144:145], v[154:155] op_sel_hi:[0,1]
	v_pk_mul_f32 v[122:123], v[122:123], v[126:127]
	v_readlane_b32 s1, v254, 30
	v_cvt_pk_bf16_f32 v121, v122, v123
	v_lshlrev_b32_e32 v122, 16, v124
	v_pk_mul_f32 v[124:125], v[116:117], v[152:153] op_sel_hi:[1,0]
	v_or_b32_sdwa v120, v122, v120 dst_sel:DWORD dst_unused:UNUSED_PAD src0_sel:DWORD src1_sel:WORD_0
	v_pk_mul_f32 v[122:123], v[118:119], v[152:153] op_sel_hi:[1,0]
	v_exp_f32_e32 v124, v124
	v_exp_f32_e32 v125, v125
	v_exp_f32_e32 v122, v122
	v_exp_f32_e32 v123, v123
	v_add_f32_e32 v124, 1.0, v124
	v_add_f32_e32 v125, 1.0, v125
	v_rcp_f32_e32 v124, v124
	v_rcp_f32_e32 v125, v125
	v_add_f32_e32 v122, 1.0, v122
	v_add_f32_e32 v123, 1.0, v123
	v_rcp_f32_e32 v122, v122
	v_rcp_f32_e32 v123, v123
	v_pk_mul_f32 v[116:117], v[144:145], v[124:125] op_sel_hi:[0,1]
	v_pk_mul_f32 v[112:113], v[112:113], v[116:117]
	v_pk_mul_f32 v[118:119], v[144:145], v[122:123] op_sel_hi:[0,1]
	v_pk_mul_f32 v[114:115], v[114:115], v[118:119]
	v_cvt_pk_bf16_f32 v122, v112, v113
	v_mov_b64_e32 v[112:113], s[0:1]
	v_cvt_pk_bf16_f32 v123, v114, v115
	v_mad_i64_i32 v[116:117], s[0:1], v138, s9, v[112:113]
	v_lshlrev_b64 v[114:115], 1, v[142:143]
	v_lshl_add_u64 v[116:117], v[116:117], 0, v[114:115]
	global_store_dwordx4 v[116:117], v[120:123], off
	v_fmamk_f32 v116, v232, 0x3a800000, v194
	v_cmp_gt_f32_e32 vcc, s2, v116
	v_mul_f32_e32 v117, 0x4b800000, v116
	s_nop 0
	v_cndmask_b32_e32 v116, v116, v117, vcc
	v_rsq_f32_e32 v116, v116
	s_nop 0
	v_mul_f32_e32 v117, 0x45800000, v116
	v_cndmask_b32_e32 v116, v116, v117, vcc
	v_mul_f32_e32 v118, 0xbfb8aa3b, v116
	v_pk_mul_f32 v[120:121], v[108:109], v[118:119] op_sel_hi:[1,0]
	v_pk_mul_f32 v[122:123], v[110:111], v[118:119] op_sel_hi:[1,0]
	v_exp_f32_e32 v117, v120
	v_mul_f32_e32 v116, v116, v116
	v_add_f32_e32 v117, 1.0, v117
	v_rcp_f32_e32 v120, v117
	v_exp_f32_e32 v117, v121
	s_nop 0
	v_add_f32_e32 v117, 1.0, v117
	v_rcp_f32_e32 v121, v117
	v_exp_f32_e32 v117, v122
	s_nop 0
	v_add_f32_e32 v117, 1.0, v117
	v_rcp_f32_e32 v122, v117
	v_exp_f32_e32 v117, v123
	s_nop 0
	v_add_f32_e32 v117, 1.0, v117
	v_rcp_f32_e32 v123, v117
	v_pk_mul_f32 v[108:109], v[116:117], v[120:121] op_sel_hi:[0,1]
	v_pk_mul_f32 v[104:105], v[104:105], v[108:109]
	v_pk_mul_f32 v[110:111], v[116:117], v[122:123] op_sel_hi:[0,1]
	v_pk_mul_f32 v[106:107], v[106:107], v[110:111]
	v_cvt_pk_bf16_f32 v108, v105, s0
	v_cvt_pk_bf16_f32 v104, v104, s0
	v_cvt_pk_bf16_f32 v105, v106, v107
	v_lshlrev_b32_e32 v106, 16, v108
	v_pk_mul_f32 v[108:109], v[100:101], v[118:119] op_sel_hi:[1,0]
	v_or_b32_sdwa v104, v106, v104 dst_sel:DWORD dst_unused:UNUSED_PAD src0_sel:DWORD src1_sel:WORD_0
	v_pk_mul_f32 v[106:107], v[102:103], v[118:119] op_sel_hi:[1,0]
	v_exp_f32_e32 v108, v108
	v_exp_f32_e32 v109, v109
	v_exp_f32_e32 v106, v106
	v_exp_f32_e32 v107, v107
	v_add_f32_e32 v108, 1.0, v108
	v_add_f32_e32 v109, 1.0, v109
	v_rcp_f32_e32 v108, v108
	v_rcp_f32_e32 v109, v109
	v_add_f32_e32 v106, 1.0, v106
	v_add_f32_e32 v107, 1.0, v107
	v_rcp_f32_e32 v106, v106
	v_rcp_f32_e32 v107, v107
	v_pk_mul_f32 v[100:101], v[116:117], v[108:109] op_sel_hi:[0,1]
	v_pk_mul_f32 v[96:97], v[96:97], v[100:101]
	v_pk_mul_f32 v[102:103], v[116:117], v[106:107] op_sel_hi:[0,1]
	v_pk_mul_f32 v[98:99], v[98:99], v[102:103]
	v_cvt_pk_bf16_f32 v106, v96, v97
	v_mad_i64_i32 v[96:97], s[0:1], v150, s9, v[112:113]
	v_cvt_pk_bf16_f32 v107, v98, v99
	v_lshl_add_u64 v[96:97], v[96:97], 0, v[114:115]
	global_store_dwordx4 v[96:97], v[104:107], off
	v_fmamk_f32 v96, v233, 0x3a800000, v194
	v_cmp_gt_f32_e32 vcc, s2, v96
	v_mul_f32_e32 v97, 0x4b800000, v96
	s_nop 0
	v_cndmask_b32_e32 v96, v96, v97, vcc
	v_rsq_f32_e32 v96, v96
	s_nop 0
	v_mul_f32_e32 v97, 0x45800000, v96
	v_cndmask_b32_e32 v97, v96, v97, vcc
	v_mul_f32_e32 v96, 0xbfb8aa3b, v97
	v_pk_mul_f32 v[102:103], v[92:93], v[96:97] op_sel_hi:[1,0]
	v_mul_f32_e32 v98, v97, v97
	v_pk_mul_f32 v[100:101], v[94:95], v[96:97] op_sel_hi:[1,0]
	v_exp_f32_e32 v97, v102
	s_nop 0
	v_add_f32_e32 v97, 1.0, v97
	v_rcp_f32_e32 v102, v97
	v_exp_f32_e32 v97, v103
	s_nop 0
	v_add_f32_e32 v97, 1.0, v97
	v_rcp_f32_e32 v103, v97
	v_exp_f32_e32 v97, v100
	v_pk_mul_f32 v[92:93], v[98:99], v[102:103] op_sel_hi:[0,1]
	v_add_f32_e32 v97, 1.0, v97
	v_rcp_f32_e32 v100, v97
	v_exp_f32_e32 v97, v101
	v_pk_mul_f32 v[88:89], v[88:89], v[92:93]
	v_add_f32_e32 v97, 1.0, v97
	v_rcp_f32_e32 v101, v97
	v_cvt_pk_bf16_f32 v92, v89, s0
	v_cvt_pk_bf16_f32 v88, v88, s0
	v_pk_mul_f32 v[94:95], v[98:99], v[100:101] op_sel_hi:[0,1]
	v_pk_mul_f32 v[90:91], v[90:91], v[94:95]
	s_nop 0
	v_cvt_pk_bf16_f32 v89, v90, v91
	v_lshlrev_b32_e32 v90, 16, v92
	v_pk_mul_f32 v[92:93], v[84:85], v[96:97] op_sel_hi:[1,0]
	v_or_b32_sdwa v88, v90, v88 dst_sel:DWORD dst_unused:UNUSED_PAD src0_sel:DWORD src1_sel:WORD_0
	v_pk_mul_f32 v[90:91], v[86:87], v[96:97] op_sel_hi:[1,0]
	v_exp_f32_e32 v92, v92
	v_exp_f32_e32 v93, v93
	v_exp_f32_e32 v90, v90
	v_exp_f32_e32 v91, v91
	v_add_f32_e32 v92, 1.0, v92
	v_add_f32_e32 v93, 1.0, v93
	v_rcp_f32_e32 v92, v92
	v_rcp_f32_e32 v93, v93
	v_add_f32_e32 v90, 1.0, v90
	v_add_f32_e32 v91, 1.0, v91
	v_rcp_f32_e32 v90, v90
	v_rcp_f32_e32 v91, v91
	v_pk_mul_f32 v[84:85], v[98:99], v[92:93] op_sel_hi:[0,1]
	v_pk_mul_f32 v[80:81], v[80:81], v[84:85]
	v_pk_mul_f32 v[86:87], v[98:99], v[90:91] op_sel_hi:[0,1]
	v_pk_mul_f32 v[82:83], v[82:83], v[86:87]
	v_cvt_pk_bf16_f32 v90, v80, v81
	v_mad_i64_i32 v[80:81], s[0:1], v148, s9, v[112:113]
	v_cvt_pk_bf16_f32 v91, v82, v83
	v_lshl_add_u64 v[80:81], v[80:81], 0, v[114:115]
	global_store_dwordx4 v[80:81], v[88:91], off
	v_fmamk_f32 v80, v234, 0x3a800000, v194
	v_cmp_gt_f32_e32 vcc, s2, v80
	v_mul_f32_e32 v81, 0x4b800000, v80
	s_nop 0
	v_cndmask_b32_e32 v80, v80, v81, vcc
	v_rsq_f32_e32 v80, v80
	s_nop 0
	v_mul_f32_e32 v81, 0x45800000, v80
	v_cndmask_b32_e32 v81, v80, v81, vcc
	v_mul_f32_e32 v80, 0xbfb8aa3b, v81
	v_pk_mul_f32 v[86:87], v[76:77], v[80:81] op_sel_hi:[1,0]
	v_mul_f32_e32 v82, v81, v81
	v_pk_mul_f32 v[84:85], v[78:79], v[80:81] op_sel_hi:[1,0]
	v_exp_f32_e32 v81, v86
	s_nop 0
	v_add_f32_e32 v81, 1.0, v81
	v_rcp_f32_e32 v86, v81
	v_exp_f32_e32 v81, v87
	s_nop 0
	v_add_f32_e32 v81, 1.0, v81
	v_rcp_f32_e32 v87, v81
	v_exp_f32_e32 v81, v84
	v_pk_mul_f32 v[76:77], v[82:83], v[86:87] op_sel_hi:[0,1]
	v_add_f32_e32 v81, 1.0, v81
	v_rcp_f32_e32 v84, v81
	v_exp_f32_e32 v81, v85
	v_pk_mul_f32 v[72:73], v[72:73], v[76:77]
	v_add_f32_e32 v81, 1.0, v81
	v_rcp_f32_e32 v85, v81
	v_cvt_pk_bf16_f32 v76, v73, s0
	v_cvt_pk_bf16_f32 v72, v72, s0
	v_pk_mul_f32 v[78:79], v[82:83], v[84:85] op_sel_hi:[0,1]
	v_pk_mul_f32 v[74:75], v[74:75], v[78:79]
	s_nop 0
	v_cvt_pk_bf16_f32 v73, v74, v75
	v_lshlrev_b32_e32 v74, 16, v76
	v_pk_mul_f32 v[76:77], v[68:69], v[80:81] op_sel_hi:[1,0]
	v_or_b32_sdwa v72, v74, v72 dst_sel:DWORD dst_unused:UNUSED_PAD src0_sel:DWORD src1_sel:WORD_0
	v_pk_mul_f32 v[74:75], v[70:71], v[80:81] op_sel_hi:[1,0]
	v_exp_f32_e32 v76, v76
	v_exp_f32_e32 v77, v77
	v_exp_f32_e32 v74, v74
	v_exp_f32_e32 v75, v75
	v_add_f32_e32 v76, 1.0, v76
	v_add_f32_e32 v77, 1.0, v77
	v_rcp_f32_e32 v76, v76
	v_rcp_f32_e32 v77, v77
	v_add_f32_e32 v74, 1.0, v74
	v_add_f32_e32 v75, 1.0, v75
	v_rcp_f32_e32 v74, v74
	v_rcp_f32_e32 v75, v75
	v_pk_mul_f32 v[68:69], v[82:83], v[76:77] op_sel_hi:[0,1]
	v_pk_mul_f32 v[64:65], v[64:65], v[68:69]
	v_add_u32_e32 v69, 0x90, v138
	v_pk_mul_f32 v[70:71], v[82:83], v[74:75] op_sel_hi:[0,1]
	v_pk_mul_f32 v[66:67], v[66:67], v[70:71]
	v_cvt_pk_bf16_f32 v74, v64, v65
	v_mad_i64_i32 v[64:65], s[0:1], v139, s9, v[112:113]
	v_cvt_pk_bf16_f32 v75, v66, v67
	v_lshl_add_u64 v[64:65], v[64:65], 0, v[114:115]
	global_store_dwordx4 v[64:65], v[72:75], off
	v_add_u32_e32 v67, 0x80, v138
	v_add_u32_e32 v66, 0xa0, v138
	v_add_u32_e32 v64, 0xb0, v138
	v_fmamk_f32 v68, v235, 0x3a800000, v194
	v_cmp_gt_f32_e32 vcc, s2, v68
	v_mul_f32_e32 v70, 0x4b800000, v68
	s_nop 0
	v_cndmask_b32_e32 v68, v68, v70, vcc
	v_rsq_f32_e32 v68, v68
	s_nop 0
	v_mul_f32_e32 v70, 0x45800000, v68
	v_cndmask_b32_e32 v70, v68, v70, vcc
	v_mul_f32_e32 v68, 0xbfb8aa3b, v70
	v_pk_mul_f32 v[74:75], v[60:61], v[68:69] op_sel_hi:[1,0]
	v_pk_mul_f32 v[72:73], v[62:63], v[68:69] op_sel_hi:[1,0]
	v_exp_f32_e32 v74, v74
	v_exp_f32_e32 v75, v75
	v_exp_f32_e32 v72, v72
	v_exp_f32_e32 v73, v73
	v_add_f32_e32 v74, 1.0, v74
	v_add_f32_e32 v75, 1.0, v75
	v_rcp_f32_e32 v74, v74
	v_rcp_f32_e32 v75, v75
	v_add_f32_e32 v72, 1.0, v72
	v_add_f32_e32 v73, 1.0, v73
	v_rcp_f32_e32 v72, v72
	v_rcp_f32_e32 v73, v73
	v_mul_f32_e32 v70, v70, v70
	v_pk_mul_f32 v[60:61], v[70:71], v[74:75] op_sel_hi:[0,1]
	v_pk_mul_f32 v[56:57], v[56:57], v[60:61]
	v_pk_mul_f32 v[62:63], v[70:71], v[72:73] op_sel_hi:[0,1]
	v_pk_mul_f32 v[58:59], v[58:59], v[62:63]
	v_cvt_pk_bf16_f32 v60, v57, s0
	v_cvt_pk_bf16_f32 v56, v56, s0
	v_cvt_pk_bf16_f32 v57, v58, v59
	v_lshlrev_b32_e32 v58, 16, v60
	v_pk_mul_f32 v[60:61], v[52:53], v[68:69] op_sel_hi:[1,0]
	v_or_b32_sdwa v56, v58, v56 dst_sel:DWORD dst_unused:UNUSED_PAD src0_sel:DWORD src1_sel:WORD_0
	v_pk_mul_f32 v[58:59], v[54:55], v[68:69] op_sel_hi:[1,0]
	v_exp_f32_e32 v60, v60
	v_exp_f32_e32 v61, v61
	v_exp_f32_e32 v58, v58
	v_exp_f32_e32 v59, v59
	v_add_f32_e32 v60, 1.0, v60
	v_add_f32_e32 v61, 1.0, v61
	v_rcp_f32_e32 v60, v60
	v_rcp_f32_e32 v61, v61
	v_add_f32_e32 v58, 1.0, v58
	v_add_f32_e32 v59, 1.0, v59
	v_rcp_f32_e32 v58, v58
	v_rcp_f32_e32 v59, v59
	v_pk_mul_f32 v[52:53], v[70:71], v[60:61] op_sel_hi:[0,1]
	v_pk_mul_f32 v[48:49], v[48:49], v[52:53]
	v_pk_mul_f32 v[54:55], v[70:71], v[58:59] op_sel_hi:[0,1]
	v_pk_mul_f32 v[50:51], v[50:51], v[54:55]
	v_cvt_pk_bf16_f32 v58, v48, v49
	v_mad_i64_i32 v[48:49], s[0:1], v67, s9, v[112:113]
	v_cvt_pk_bf16_f32 v59, v50, v51
	v_lshl_add_u64 v[48:49], v[48:49], 0, v[114:115]
	global_store_dwordx4 v[48:49], v[56:59], off
	v_fmamk_f32 v48, v236, 0x3a800000, v194
	v_cmp_gt_f32_e32 vcc, s2, v48
	v_mul_f32_e32 v49, 0x4b800000, v48
	s_nop 0
	v_cndmask_b32_e32 v48, v48, v49, vcc
	v_rsq_f32_e32 v48, v48
	s_nop 0
	v_mul_f32_e32 v49, 0x45800000, v48
	v_cndmask_b32_e32 v49, v48, v49, vcc
	v_mul_f32_e32 v48, 0xbfb8aa3b, v49
	v_pk_mul_f32 v[54:55], v[44:45], v[48:49] op_sel_hi:[1,0]
	v_mul_f32_e32 v50, v49, v49
	v_pk_mul_f32 v[52:53], v[46:47], v[48:49] op_sel_hi:[1,0]
	v_exp_f32_e32 v49, v54
	s_nop 0
	v_add_f32_e32 v49, 1.0, v49
	v_rcp_f32_e32 v54, v49
	v_exp_f32_e32 v49, v55
	s_nop 0
	v_add_f32_e32 v49, 1.0, v49
	v_rcp_f32_e32 v55, v49
	v_exp_f32_e32 v49, v52
	v_pk_mul_f32 v[44:45], v[50:51], v[54:55] op_sel_hi:[0,1]
	v_add_f32_e32 v49, 1.0, v49
	v_rcp_f32_e32 v52, v49
	v_exp_f32_e32 v49, v53
	v_pk_mul_f32 v[40:41], v[40:41], v[44:45]
	v_add_f32_e32 v49, 1.0, v49
	v_rcp_f32_e32 v53, v49
	v_cvt_pk_bf16_f32 v44, v41, s0
	v_cvt_pk_bf16_f32 v40, v40, s0
	v_pk_mul_f32 v[46:47], v[50:51], v[52:53] op_sel_hi:[0,1]
	v_pk_mul_f32 v[42:43], v[42:43], v[46:47]
	s_nop 0
	v_cvt_pk_bf16_f32 v41, v42, v43
	v_lshlrev_b32_e32 v42, 16, v44
	v_pk_mul_f32 v[44:45], v[36:37], v[48:49] op_sel_hi:[1,0]
	v_or_b32_sdwa v40, v42, v40 dst_sel:DWORD dst_unused:UNUSED_PAD src0_sel:DWORD src1_sel:WORD_0
	v_pk_mul_f32 v[42:43], v[38:39], v[48:49] op_sel_hi:[1,0]
	v_exp_f32_e32 v44, v44
	v_exp_f32_e32 v45, v45
	v_exp_f32_e32 v42, v42
	v_exp_f32_e32 v43, v43
	v_add_f32_e32 v44, 1.0, v44
	v_add_f32_e32 v45, 1.0, v45
	v_rcp_f32_e32 v44, v44
	v_rcp_f32_e32 v45, v45
	v_add_f32_e32 v42, 1.0, v42
	v_add_f32_e32 v43, 1.0, v43
	v_rcp_f32_e32 v42, v42
	v_rcp_f32_e32 v43, v43
	v_pk_mul_f32 v[36:37], v[50:51], v[44:45] op_sel_hi:[0,1]
	v_pk_mul_f32 v[32:33], v[32:33], v[36:37]
	v_pk_mul_f32 v[38:39], v[50:51], v[42:43] op_sel_hi:[0,1]
	v_pk_mul_f32 v[34:35], v[34:35], v[38:39]
	v_cvt_pk_bf16_f32 v42, v32, v33
	v_mad_i64_i32 v[32:33], s[0:1], v69, s9, v[112:113]
	v_cvt_pk_bf16_f32 v43, v34, v35
	v_lshl_add_u64 v[32:33], v[32:33], 0, v[114:115]
	global_store_dwordx4 v[32:33], v[40:43], off
	v_fmamk_f32 v32, v237, 0x3a800000, v194
	v_cmp_gt_f32_e32 vcc, s2, v32
	v_mul_f32_e32 v33, 0x4b800000, v32
	s_nop 0
	v_cndmask_b32_e32 v32, v32, v33, vcc
	v_rsq_f32_e32 v32, v32
	s_nop 0
	v_mul_f32_e32 v33, 0x45800000, v32
	v_cndmask_b32_e32 v33, v32, v33, vcc
	v_mul_f32_e32 v32, 0xbfb8aa3b, v33
	v_pk_mul_f32 v[38:39], v[28:29], v[32:33] op_sel_hi:[1,0]
	v_mul_f32_e32 v34, v33, v33
	v_pk_mul_f32 v[36:37], v[30:31], v[32:33] op_sel_hi:[1,0]
	v_exp_f32_e32 v33, v38
	s_nop 0
	v_add_f32_e32 v33, 1.0, v33
	v_rcp_f32_e32 v38, v33
	v_exp_f32_e32 v33, v39
	s_nop 0
	v_add_f32_e32 v33, 1.0, v33
	v_rcp_f32_e32 v39, v33
	v_exp_f32_e32 v33, v36
	v_pk_mul_f32 v[28:29], v[34:35], v[38:39] op_sel_hi:[0,1]
	v_add_f32_e32 v33, 1.0, v33
	v_rcp_f32_e32 v36, v33
	v_exp_f32_e32 v33, v37
	v_pk_mul_f32 v[24:25], v[24:25], v[28:29]
	v_add_f32_e32 v33, 1.0, v33
	v_rcp_f32_e32 v37, v33
	v_cvt_pk_bf16_f32 v28, v25, s0
	v_cvt_pk_bf16_f32 v24, v24, s0
	v_pk_mul_f32 v[30:31], v[34:35], v[36:37] op_sel_hi:[0,1]
	v_pk_mul_f32 v[26:27], v[26:27], v[30:31]
	s_nop 0
	v_cvt_pk_bf16_f32 v25, v26, v27
	v_lshlrev_b32_e32 v26, 16, v28
	v_pk_mul_f32 v[28:29], v[20:21], v[32:33] op_sel_hi:[1,0]
	v_or_b32_sdwa v24, v26, v24 dst_sel:DWORD dst_unused:UNUSED_PAD src0_sel:DWORD src1_sel:WORD_0
	v_pk_mul_f32 v[26:27], v[22:23], v[32:33] op_sel_hi:[1,0]
	v_exp_f32_e32 v28, v28
	v_exp_f32_e32 v29, v29
	v_exp_f32_e32 v26, v26
	v_exp_f32_e32 v27, v27
	v_add_f32_e32 v28, 1.0, v28
	v_add_f32_e32 v29, 1.0, v29
	v_rcp_f32_e32 v28, v28
	v_rcp_f32_e32 v29, v29
	v_add_f32_e32 v26, 1.0, v26
	v_add_f32_e32 v27, 1.0, v27
	v_rcp_f32_e32 v26, v26
	v_rcp_f32_e32 v27, v27
	v_pk_mul_f32 v[20:21], v[34:35], v[28:29] op_sel_hi:[0,1]
	v_pk_mul_f32 v[16:17], v[16:17], v[20:21]
	v_pk_mul_f32 v[22:23], v[34:35], v[26:27] op_sel_hi:[0,1]
	v_pk_mul_f32 v[18:19], v[18:19], v[22:23]
	v_cvt_pk_bf16_f32 v26, v16, v17
	v_mad_i64_i32 v[16:17], s[0:1], v66, s9, v[112:113]
	v_cvt_pk_bf16_f32 v27, v18, v19
	v_lshl_add_u64 v[16:17], v[16:17], 0, v[114:115]
	global_store_dwordx4 v[16:17], v[24:27], off
	v_fmamk_f32 v16, v238, 0x3a800000, v194
	v_cmp_gt_f32_e32 vcc, s2, v16
	v_mul_f32_e32 v17, 0x4b800000, v16
	s_nop 0
	v_cndmask_b32_e32 v16, v16, v17, vcc
	v_rsq_f32_e32 v16, v16
	s_nop 0
	v_mul_f32_e32 v17, 0x45800000, v16
	v_cndmask_b32_e32 v17, v16, v17, vcc
	v_mul_f32_e32 v16, 0xbfb8aa3b, v17
	v_pk_mul_f32 v[22:23], v[12:13], v[16:17] op_sel_hi:[1,0]
	v_mul_f32_e32 v18, v17, v17
	v_pk_mul_f32 v[20:21], v[14:15], v[16:17] op_sel_hi:[1,0]
	v_exp_f32_e32 v17, v22
	s_and_b64 vcc, exec, s[4:5]
	v_add_f32_e32 v17, 1.0, v17
	v_rcp_f32_e32 v22, v17
	v_exp_f32_e32 v17, v23
	s_nop 0
	v_add_f32_e32 v17, 1.0, v17
	v_rcp_f32_e32 v23, v17
	v_exp_f32_e32 v17, v20
	v_pk_mul_f32 v[12:13], v[18:19], v[22:23] op_sel_hi:[0,1]
	v_add_f32_e32 v17, 1.0, v17
	v_rcp_f32_e32 v20, v17
	v_exp_f32_e32 v17, v21
	v_pk_mul_f32 v[8:9], v[8:9], v[12:13]
	v_add_f32_e32 v17, 1.0, v17
	v_rcp_f32_e32 v21, v17
	v_cvt_pk_bf16_f32 v12, v9, s0
	v_cvt_pk_bf16_f32 v8, v8, s0
	v_pk_mul_f32 v[14:15], v[18:19], v[20:21] op_sel_hi:[0,1]
	v_pk_mul_f32 v[10:11], v[10:11], v[14:15]
	s_nop 0
	v_cvt_pk_bf16_f32 v9, v10, v11
	v_lshlrev_b32_e32 v10, 16, v12
	v_pk_mul_f32 v[12:13], v[4:5], v[16:17] op_sel_hi:[1,0]
	v_or_b32_sdwa v8, v10, v8 dst_sel:DWORD dst_unused:UNUSED_PAD src0_sel:DWORD src1_sel:WORD_0
	v_pk_mul_f32 v[10:11], v[6:7], v[16:17] op_sel_hi:[1,0]
	v_exp_f32_e32 v12, v12
	v_exp_f32_e32 v13, v13
	v_exp_f32_e32 v10, v10
	v_exp_f32_e32 v11, v11
	v_add_f32_e32 v12, 1.0, v12
	v_add_f32_e32 v13, 1.0, v13
	v_rcp_f32_e32 v12, v12
	v_rcp_f32_e32 v13, v13
	v_add_f32_e32 v10, 1.0, v10
	v_add_f32_e32 v11, 1.0, v11
	v_rcp_f32_e32 v10, v10
	v_rcp_f32_e32 v11, v11
	v_pk_mul_f32 v[4:5], v[18:19], v[12:13] op_sel_hi:[0,1]
	v_pk_mul_f32 v[0:1], v[0:1], v[4:5]
	v_pk_mul_f32 v[6:7], v[18:19], v[10:11] op_sel_hi:[0,1]
	v_pk_mul_f32 v[2:3], v[2:3], v[6:7]
	v_cvt_pk_bf16_f32 v10, v0, v1
	v_mad_i64_i32 v[0:1], s[0:1], v64, s9, v[112:113]
	v_cvt_pk_bf16_f32 v11, v2, v3
	v_lshl_add_u64 v[0:1], v[0:1], 0, v[114:115]
	s_mov_b32 s0, s10
	global_store_dwordx4 v[0:1], v[8:11], off
	s_cbranch_vccz .LBB0_399
	s_waitcnt vmcnt(0)
	s_cmpk_gt_u32 s25, 0xff
	s_cbranch_scc1 .LBB0_406
	s_barrier

.LBB0_2801:
	v_lshrrev_b32_e32 v250, 8, v252
	v_lshlrev_b32_e32 v250, 6, v250
	v_and_or_b32 v250, v252, 15, v250
	v_lshl_add_u32 v250, s16, 8, v250
	v_mov_b32_e32 v251, 0
	v_lshl_add_u64 v[248:249], v[250:251], 2, s[6:7]
	global_load_dword v231, v[248:249], off
	global_load_dword v232, v[248:249], off offset:64
	global_load_dword v233, v[248:249], off offset:128
	global_load_dword v234, v[248:249], off offset:192
	global_load_dword v235, v[248:249], off offset:512
	global_load_dword v236, v[248:249], off offset:576
	global_load_dword v237, v[248:249], off offset:640
	global_load_dword v238, v[248:249], off offset:704
	s_add_i32 s36, s36, 1
	v_readlane_b32 s0, v254, 22
	v_readlane_b32 s9, v253, 15
	s_mul_i32 s0, s36, s0
	s_mul_hi_u32 s1, s36, s9
	s_add_i32 s1, s1, s0
	s_mul_i32 s0, s36, s9
	s_mov_b32 s9, s87
	v_readlane_b32 s11, v254, 3
	s_mul_hi_u32 s11, s9, s11
	s_mul_i32 s11, s11, s78
	s_sub_i32 s9, s9, s11
	s_sub_i32 s11, s9, s78
	s_cmp_ge_u32 s9, s78
	s_cselect_b32 s9, s11, s9
	s_sub_i32 s11, s9, s78
	s_cmp_ge_u32 s9, s78
	s_cselect_b32 s9, s11, s9
	s_ashr_i32 s11, s9, 31
	s_add_u32 s12, s0, s9
	s_addc_u32 s13, s1, s11
	v_mov_b64_e32 v[0:1], 0x57f
	v_cmp_gt_i64_e64 s[0:1], s[12:13], v[0:1]
	s_and_b64 vcc, exec, s[0:1]
	s_cbranch_vccnz .LBB0_2803
	s_ashr_i32 s8, s12, 31
	s_lshr_b32 s8, s8, 29
	s_add_i32 s8, s12, s8
	s_ashr_i32 s9, s8, 3
	s_and_b32 s8, s8, -8
	s_sub_i32 s8, s12, s8
	s_lshr_b32 s10, s8, 31
	s_or_b32 s10, s10, 0xb0
	s_mul_i32 s8, s10, s8
	s_add_i32 s8, s8, s9
	s_mul_hi_i32 s9, s8, 0x2e8ba2e9
	s_lshr_b32 s10, s9, 31
	s_ashr_i32 s9, s9, 4
	s_add_i32 s9, s9, s10
	s_lshl_b32 s11, s9, 2
	s_sub_i32 s10, 64, s11
	s_min_i32 s14, s10, 4
	s_abs_i32 s10, s14
	v_cvt_f32_u32_e32 v0, s10
	s_sub_i32 s22, 0, s10
	s_mulk_i32 s9, 0x58
	s_sub_i32 s8, s8, s9
	v_rcp_iflag_f32_e32 v0, v0
	s_abs_i32 s9, s8
	s_xor_b32 s15, s8, s14
	s_ashr_i32 s15, s15, 31
	v_mul_f32_e32 v0, 0x4f7ffffe, v0
	v_cvt_u32_f32_e32 v0, v0
	s_nop 0
	v_readfirstlane_b32 s23, v0
	s_mul_i32 s22, s22, s23
	s_mul_hi_u32 s22, s23, s22
	s_add_i32 s23, s23, s22
	s_mul_hi_u32 s22, s9, s23
	s_mul_i32 s23, s22, s10
	s_sub_i32 s9, s9, s23
	s_add_i32 s33, s22, 1
	s_sub_i32 s23, s9, s10
	s_cmp_ge_u32 s9, s10
	s_cselect_b32 s22, s33, s22
	s_cselect_b32 s9, s23, s9
	s_add_i32 s23, s22, 1
	s_cmp_ge_u32 s9, s10
	s_cselect_b32 s9, s23, s22
	s_xor_b32 s9, s9, s15
	s_sub_i32 s10, s9, s15
	s_mul_i32 s9, s10, s14
	s_sub_i32 s8, s8, s9
	s_add_i32 s8, s8, s11

.LBB0_2804:
	s_add_u32 s20, s18, 0xfffc0080
	s_addc_u32 s21, s19, -1
	s_add_i32 s42, 0, 0x10000
	v_add_u32_e32 v150, s42, v151
	ds_read_b128 v[138:141], v150
	ds_read_b128 v[142:145], v150 offset:1024
	ds_read_b128 v[146:149], v150 offset:2048
	ds_read_b128 v[154:157], v150 offset:3072
	s_cmp_eq_u32 s41, 12
	s_cselect_b32 s23, s9, s21
	s_cselect_b32 s22, s33, s20
	s_cselect_b32 s21, s11, s40
	s_cselect_b32 s20, s38, s39
	v_lshl_add_u64 v[190:191], s[18:19], 0, v[136:137]
	s_add_i32 m0, s17, 0xc000
	ds_read_b128 v[158:161], v152
	ds_read_b128 v[162:165], v152 offset:1024
	ds_read_b128 v[166:169], v152 offset:2048
	ds_read_b128 v[170:173], v152 offset:3072
	ds_read_b128 v[174:177], v152 offset:4096
	ds_read_b128 v[178:181], v152 offset:5120
	ds_read_b128 v[182:185], v152 offset:6144
	ds_read_b128 v[186:189], v152 offset:7168
	global_load_lds_dwordx4 v[190:191], off
	v_lshl_add_u64 v[190:191], s[18:19], 0, v[134:135]
	s_add_i32 m0, s17, 0xe000
	s_nop 0
	global_load_lds_dwordx4 v[190:191], off
	s_waitcnt lgkmcnt(8)
	s_barrier
	s_waitcnt lgkmcnt(0)
	s_setprio 1
	s_waitcnt lgkmcnt(0)
	v_mfma_f32_16x16x32_bf16 v[124:127], v[138:141], v[158:161], v[124:127]
	v_mfma_f32_16x16x32_bf16 v[116:119], v[146:149], v[158:161], v[116:119]
	v_mfma_f32_16x16x32_bf16 v[108:111], v[138:141], v[166:169], v[108:111]
	v_mfma_f32_16x16x32_bf16 v[100:103], v[146:149], v[166:169], v[100:103]
	v_mfma_f32_16x16x32_bf16 v[92:95], v[138:141], v[174:177], v[92:95]
	v_mfma_f32_16x16x32_bf16 v[84:87], v[146:149], v[174:177], v[84:87]
	v_mfma_f32_16x16x32_bf16 v[76:79], v[138:141], v[182:185], v[76:79]
	v_mfma_f32_16x16x32_bf16 v[68:71], v[146:149], v[182:185], v[68:71]
	v_mfma_f32_16x16x32_bf16 v[124:127], v[142:145], v[162:165], v[124:127]
	v_mfma_f32_16x16x32_bf16 v[116:119], v[154:157], v[162:165], v[116:119]
	v_mfma_f32_16x16x32_bf16 v[108:111], v[142:145], v[170:173], v[108:111]
	v_mfma_f32_16x16x32_bf16 v[100:103], v[154:157], v[170:173], v[100:103]
	v_mfma_f32_16x16x32_bf16 v[92:95], v[142:145], v[178:181], v[92:95]
	v_mfma_f32_16x16x32_bf16 v[84:87], v[154:157], v[178:181], v[84:87]
	v_mfma_f32_16x16x32_bf16 v[76:79], v[142:145], v[186:189], v[76:79]
	v_mfma_f32_16x16x32_bf16 v[68:71], v[154:157], v[186:189], v[68:71]
	s_setprio 0
	s_barrier
	s_add_i32 s44, 0, 0x14000
	s_add_i32 s42, s42, s28
	v_add_u32_e32 v150, s44, v151
	v_lshl_add_u64 v[190:191], s[20:21], 0, v[192:193]
	s_mov_b32 m0, s42
	ds_read_b128 v[198:201], v150
	ds_read_b128 v[206:209], v150 offset:1024
	ds_read_b128 v[210:213], v150 offset:2048
	ds_read_b128 v[214:217], v150 offset:3072
	global_load_lds_dwordx4 v[190:191], off
	v_lshl_add_u64 v[202:203], s[20:21], 0, v[128:129]
	s_add_i32 m0, s42, 0x2000
	s_nop 0
	global_load_lds_dwordx4 v[202:203], off
	s_barrier
	s_waitcnt lgkmcnt(0)
	s_setprio 1
	s_waitcnt lgkmcnt(0)
	v_mfma_f32_16x16x32_bf16 v[120:123], v[198:201], v[158:161], v[120:123]
	v_mfma_f32_16x16x32_bf16 v[112:115], v[210:213], v[158:161], v[112:115]
	v_mfma_f32_16x16x32_bf16 v[104:107], v[198:201], v[166:169], v[104:107]
	v_mfma_f32_16x16x32_bf16 v[96:99], v[210:213], v[166:169], v[96:99]
	v_mfma_f32_16x16x32_bf16 v[88:91], v[198:201], v[174:177], v[88:91]
	v_mfma_f32_16x16x32_bf16 v[80:83], v[210:213], v[174:177], v[80:83]
	v_mfma_f32_16x16x32_bf16 v[72:75], v[198:201], v[182:185], v[72:75]
	v_mfma_f32_16x16x32_bf16 v[64:67], v[210:213], v[182:185], v[64:67]
	v_mfma_f32_16x16x32_bf16 v[120:123], v[206:209], v[162:165], v[120:123]
	v_mfma_f32_16x16x32_bf16 v[112:115], v[214:217], v[162:165], v[112:115]
	v_mfma_f32_16x16x32_bf16 v[104:107], v[206:209], v[170:173], v[104:107]
	v_mfma_f32_16x16x32_bf16 v[96:99], v[214:217], v[170:173], v[96:99]
	v_mfma_f32_16x16x32_bf16 v[88:91], v[206:209], v[178:181], v[88:91]
	v_mfma_f32_16x16x32_bf16 v[80:83], v[214:217], v[178:181], v[80:83]
	v_mfma_f32_16x16x32_bf16 v[72:75], v[206:209], v[186:189], v[72:75]
	v_mfma_f32_16x16x32_bf16 v[64:67], v[214:217], v[186:189], v[64:67]
	s_setprio 0
	s_mov_b32 m0, s17
	v_lshl_add_u64 v[204:205], s[22:23], 0, v[132:133]
	s_barrier
	ds_read_b128 v[158:161], v152 offset:16384
	ds_read_b128 v[162:165], v152 offset:17408
	ds_read_b128 v[166:169], v152 offset:18432
	ds_read_b128 v[170:173], v152 offset:19456
	ds_read_b128 v[174:177], v152 offset:20480
	ds_read_b128 v[178:181], v152 offset:21504
	ds_read_b128 v[182:185], v152 offset:22528
	ds_read_b128 v[186:189], v152 offset:23552
	global_load_lds_dwordx4 v[204:205], off
	v_lshl_add_u64 v[218:219], s[22:23], 0, v[130:131]
	s_mov_b32 m0, s29
	s_nop 0
	global_load_lds_dwordx4 v[218:219], off
	s_barrier
	s_waitcnt lgkmcnt(0)
	s_setprio 1
	s_waitcnt lgkmcnt(0)
	v_mfma_f32_16x16x32_bf16 v[60:63], v[138:141], v[158:161], v[60:63]
	v_mfma_f32_16x16x32_bf16 v[52:55], v[146:149], v[158:161], v[52:55]
	v_mfma_f32_16x16x32_bf16 v[44:47], v[138:141], v[166:169], v[44:47]
	v_mfma_f32_16x16x32_bf16 v[36:39], v[146:149], v[166:169], v[36:39]
	v_mfma_f32_16x16x32_bf16 v[28:31], v[138:141], v[174:177], v[28:31]
	v_mfma_f32_16x16x32_bf16 v[20:23], v[146:149], v[174:177], v[20:23]
	v_mfma_f32_16x16x32_bf16 v[12:15], v[138:141], v[182:185], v[12:15]
	v_mfma_f32_16x16x32_bf16 v[4:7], v[146:149], v[182:185], v[4:7]
	v_mfma_f32_16x16x32_bf16 v[60:63], v[142:145], v[162:165], v[60:63]
	v_mfma_f32_16x16x32_bf16 v[52:55], v[154:157], v[162:165], v[52:55]
	v_mfma_f32_16x16x32_bf16 v[44:47], v[142:145], v[170:173], v[44:47]
	v_mfma_f32_16x16x32_bf16 v[36:39], v[154:157], v[170:173], v[36:39]
	v_mfma_f32_16x16x32_bf16 v[28:31], v[142:145], v[178:181], v[28:31]
	v_mfma_f32_16x16x32_bf16 v[20:23], v[154:157], v[178:181], v[20:23]
	v_mfma_f32_16x16x32_bf16 v[12:15], v[142:145], v[186:189], v[12:15]
	v_mfma_f32_16x16x32_bf16 v[4:7], v[154:157], v[186:189], v[4:7]
	s_setprio 0
	s_barrier
	s_add_u32 s42, s20, 0x40000
	s_addc_u32 s43, s21, 0
	s_add_i32 s44, s44, s28
	v_lshl_add_u64 v[138:139], s[42:43], 0, v[192:193]
	s_mov_b32 m0, s44
	s_nop 0
	global_load_lds_dwordx4 v[138:139], off
	v_lshl_add_u64 v[138:139], s[42:43], 0, v[128:129]
	s_add_i32 m0, s44, 0x2000
	s_nop 0
	global_load_lds_dwordx4 v[138:139], off
	s_waitcnt vmcnt(6)
	s_barrier
	s_setprio 1
	v_mfma_f32_16x16x32_bf16 v[56:59], v[198:201], v[158:161], v[56:59]
	v_mfma_f32_16x16x32_bf16 v[48:51], v[210:213], v[158:161], v[48:51]
	v_mfma_f32_16x16x32_bf16 v[40:43], v[198:201], v[166:169], v[40:43]
	v_mfma_f32_16x16x32_bf16 v[32:35], v[210:213], v[166:169], v[32:35]
	v_mfma_f32_16x16x32_bf16 v[24:27], v[198:201], v[174:177], v[24:27]
	v_mfma_f32_16x16x32_bf16 v[16:19], v[210:213], v[174:177], v[16:19]
	v_mfma_f32_16x16x32_bf16 v[8:11], v[198:201], v[182:185], v[8:11]
	v_mfma_f32_16x16x32_bf16 v[0:3], v[210:213], v[182:185], v[0:3]
	v_mfma_f32_16x16x32_bf16 v[56:59], v[206:209], v[162:165], v[56:59]
	v_mfma_f32_16x16x32_bf16 v[48:51], v[214:217], v[162:165], v[48:51]
	v_mfma_f32_16x16x32_bf16 v[40:43], v[206:209], v[170:173], v[40:43]
	v_mfma_f32_16x16x32_bf16 v[32:35], v[214:217], v[170:173], v[32:35]
	v_mfma_f32_16x16x32_bf16 v[24:27], v[206:209], v[178:181], v[24:27]
	v_mfma_f32_16x16x32_bf16 v[16:19], v[214:217], v[178:181], v[16:19]
	v_mfma_f32_16x16x32_bf16 v[8:11], v[206:209], v[186:189], v[8:11]
	v_mfma_f32_16x16x32_bf16 v[0:3], v[214:217], v[186:189], v[0:3]
	s_setprio 0
	s_add_i32 s42, 0, 0x18000
	v_add_u32_e32 v150, s42, v151
	s_barrier
	ds_read_b128 v[138:141], v150
	ds_read_b128 v[142:145], v150 offset:1024
	ds_read_b128 v[146:149], v150 offset:2048
	ds_read_b128 v[154:157], v150 offset:3072
	s_add_u32 s22, s22, 0x40000
	s_addc_u32 s23, s23, 0
	s_mov_b32 m0, s30
	v_lshl_add_u64 v[198:199], s[22:23], 0, v[132:133]
	ds_read_b128 v[158:161], v152 offset:32768
	ds_read_b128 v[162:165], v152 offset:33792
	ds_read_b128 v[166:169], v152 offset:34816
	ds_read_b128 v[170:173], v152 offset:35840
	ds_read_b128 v[174:177], v152 offset:36864
	ds_read_b128 v[178:181], v152 offset:37888
	ds_read_b128 v[182:185], v152 offset:38912
	ds_read_b128 v[186:189], v152 offset:39936
	global_load_lds_dwordx4 v[198:199], off
	v_lshl_add_u64 v[198:199], s[22:23], 0, v[130:131]
	s_mov_b32 m0, s31
	s_nop 0
	global_load_lds_dwordx4 v[198:199], off
	s_waitcnt lgkmcnt(8)
	s_barrier
	s_waitcnt lgkmcnt(0)
	s_setprio 1
	s_waitcnt lgkmcnt(0)
	v_mfma_f32_16x16x32_bf16 v[124:127], v[138:141], v[158:161], v[124:127]
	v_mfma_f32_16x16x32_bf16 v[116:119], v[146:149], v[158:161], v[116:119]
	v_mfma_f32_16x16x32_bf16 v[108:111], v[138:141], v[166:169], v[108:111]
	v_mfma_f32_16x16x32_bf16 v[100:103], v[146:149], v[166:169], v[100:103]
	v_mfma_f32_16x16x32_bf16 v[92:95], v[138:141], v[174:177], v[92:95]
	v_mfma_f32_16x16x32_bf16 v[84:87], v[146:149], v[174:177], v[84:87]
	v_mfma_f32_16x16x32_bf16 v[76:79], v[138:141], v[182:185], v[76:79]
	v_mfma_f32_16x16x32_bf16 v[68:71], v[146:149], v[182:185], v[68:71]
	v_mfma_f32_16x16x32_bf16 v[124:127], v[142:145], v[162:165], v[124:127]
	v_mfma_f32_16x16x32_bf16 v[116:119], v[154:157], v[162:165], v[116:119]
	v_mfma_f32_16x16x32_bf16 v[108:111], v[142:145], v[170:173], v[108:111]
	v_mfma_f32_16x16x32_bf16 v[100:103], v[154:157], v[170:173], v[100:103]
	v_mfma_f32_16x16x32_bf16 v[92:95], v[142:145], v[178:181], v[92:95]
	v_mfma_f32_16x16x32_bf16 v[84:87], v[154:157], v[178:181], v[84:87]
	v_mfma_f32_16x16x32_bf16 v[76:79], v[142:145], v[186:189], v[76:79]
	v_mfma_f32_16x16x32_bf16 v[68:71], v[154:157], v[186:189], v[68:71]
	s_setprio 0
	s_barrier
	s_add_i32 s22, 0, 0x1c000
	s_add_i32 s23, s42, s28
	v_add_u32_e32 v150, s22, v151
	v_lshl_add_u64 v[190:191], v[190:191], 0, s[80:81]
	s_mov_b32 m0, s23
	ds_read_b128 v[198:201], v150
	ds_read_b128 v[206:209], v150 offset:1024
	ds_read_b128 v[210:213], v150 offset:2048
	ds_read_b128 v[214:217], v150 offset:3072
	global_load_lds_dwordx4 v[190:191], off
	v_lshl_add_u64 v[190:191], v[202:203], 0, s[80:81]
	s_add_i32 m0, s23, 0x2000
	s_nop 0
	global_load_lds_dwordx4 v[190:191], off
	s_barrier
	s_waitcnt lgkmcnt(0)
	s_setprio 1
	s_waitcnt lgkmcnt(0)
	v_mfma_f32_16x16x32_bf16 v[120:123], v[198:201], v[158:161], v[120:123]
	v_mfma_f32_16x16x32_bf16 v[112:115], v[210:213], v[158:161], v[112:115]
	v_mfma_f32_16x16x32_bf16 v[104:107], v[198:201], v[166:169], v[104:107]
	v_mfma_f32_16x16x32_bf16 v[96:99], v[210:213], v[166:169], v[96:99]
	v_mfma_f32_16x16x32_bf16 v[88:91], v[198:201], v[174:177], v[88:91]
	v_mfma_f32_16x16x32_bf16 v[80:83], v[210:213], v[174:177], v[80:83]
	v_mfma_f32_16x16x32_bf16 v[72:75], v[198:201], v[182:185], v[72:75]
	v_mfma_f32_16x16x32_bf16 v[64:67], v[210:213], v[182:185], v[64:67]
	v_mfma_f32_16x16x32_bf16 v[120:123], v[206:209], v[162:165], v[120:123]
	v_mfma_f32_16x16x32_bf16 v[112:115], v[214:217], v[162:165], v[112:115]
	v_mfma_f32_16x16x32_bf16 v[104:107], v[206:209], v[170:173], v[104:107]
	v_mfma_f32_16x16x32_bf16 v[96:99], v[214:217], v[170:173], v[96:99]
	v_mfma_f32_16x16x32_bf16 v[88:91], v[206:209], v[178:181], v[88:91]
	v_mfma_f32_16x16x32_bf16 v[80:83], v[214:217], v[178:181], v[80:83]
	v_mfma_f32_16x16x32_bf16 v[72:75], v[206:209], v[186:189], v[72:75]
	v_mfma_f32_16x16x32_bf16 v[64:67], v[214:217], v[186:189], v[64:67]
	s_setprio 0
	s_mov_b32 m0, s34
	v_lshl_add_u64 v[190:191], v[204:205], 0, s[80:81]
	s_barrier
	ds_read_b128 v[158:161], v152 offset:49152
	ds_read_b128 v[162:165], v152 offset:50176
	ds_read_b128 v[166:169], v152 offset:51200
	ds_read_b128 v[170:173], v152 offset:52224
	ds_read_b128 v[174:177], v152 offset:53248
	ds_read_b128 v[178:181], v152 offset:54272
	ds_read_b128 v[182:185], v152 offset:55296
	ds_read_b128 v[186:189], v152 offset:56320
	global_load_lds_dwordx4 v[190:191], off
	v_lshl_add_u64 v[190:191], v[218:219], 0, s[80:81]
	s_mov_b32 m0, s35
	s_nop 0
	global_load_lds_dwordx4 v[190:191], off
	s_barrier
	s_waitcnt lgkmcnt(0)
	s_setprio 1
	s_waitcnt lgkmcnt(0)
	v_mfma_f32_16x16x32_bf16 v[60:63], v[138:141], v[158:161], v[60:63]
	v_mfma_f32_16x16x32_bf16 v[52:55], v[146:149], v[158:161], v[52:55]
	v_mfma_f32_16x16x32_bf16 v[44:47], v[138:141], v[166:169], v[44:47]
	v_mfma_f32_16x16x32_bf16 v[36:39], v[146:149], v[166:169], v[36:39]
	v_mfma_f32_16x16x32_bf16 v[28:31], v[138:141], v[174:177], v[28:31]
	v_mfma_f32_16x16x32_bf16 v[20:23], v[146:149], v[174:177], v[20:23]
	v_mfma_f32_16x16x32_bf16 v[12:15], v[138:141], v[182:185], v[12:15]
	v_mfma_f32_16x16x32_bf16 v[4:7], v[146:149], v[182:185], v[4:7]
	v_mfma_f32_16x16x32_bf16 v[60:63], v[142:145], v[162:165], v[60:63]
	v_mfma_f32_16x16x32_bf16 v[52:55], v[154:157], v[162:165], v[52:55]
	v_mfma_f32_16x16x32_bf16 v[44:47], v[142:145], v[170:173], v[44:47]
	v_mfma_f32_16x16x32_bf16 v[36:39], v[154:157], v[170:173], v[36:39]
	v_mfma_f32_16x16x32_bf16 v[28:31], v[142:145], v[178:181], v[28:31]
	v_mfma_f32_16x16x32_bf16 v[20:23], v[154:157], v[178:181], v[20:23]
	v_mfma_f32_16x16x32_bf16 v[12:15], v[142:145], v[186:189], v[12:15]
	v_mfma_f32_16x16x32_bf16 v[4:7], v[154:157], v[186:189], v[4:7]
	s_setprio 0
	s_barrier
	s_add_u32 s20, s20, 0x40080
	s_addc_u32 s21, s21, 0
	s_add_i32 s22, s22, s28
	v_lshl_add_u64 v[138:139], s[20:21], 0, v[192:193]
	s_mov_b32 m0, s22
	s_nop 0
	global_load_lds_dwordx4 v[138:139], off
	v_lshl_add_u64 v[138:139], s[20:21], 0, v[128:129]
	s_add_i32 m0, s22, 0x2000
	s_nop 0
	global_load_lds_dwordx4 v[138:139], off
	s_waitcnt vmcnt(6)
	s_barrier
	s_setprio 1
	v_mfma_f32_16x16x32_bf16 v[56:59], v[198:201], v[158:161], v[56:59]
	v_mfma_f32_16x16x32_bf16 v[48:51], v[210:213], v[158:161], v[48:51]
	v_mfma_f32_16x16x32_bf16 v[40:43], v[198:201], v[166:169], v[40:43]
	v_mfma_f32_16x16x32_bf16 v[32:35], v[210:213], v[166:169], v[32:35]
	v_mfma_f32_16x16x32_bf16 v[24:27], v[198:201], v[174:177], v[24:27]
	v_mfma_f32_16x16x32_bf16 v[16:19], v[210:213], v[174:177], v[16:19]
	v_mfma_f32_16x16x32_bf16 v[8:11], v[198:201], v[182:185], v[8:11]
	v_mfma_f32_16x16x32_bf16 v[0:3], v[210:213], v[182:185], v[0:3]
	v_mfma_f32_16x16x32_bf16 v[56:59], v[206:209], v[162:165], v[56:59]
	v_mfma_f32_16x16x32_bf16 v[48:51], v[214:217], v[162:165], v[48:51]
	v_mfma_f32_16x16x32_bf16 v[40:43], v[206:209], v[170:173], v[40:43]
	v_mfma_f32_16x16x32_bf16 v[32:35], v[214:217], v[170:173], v[32:35]
	v_mfma_f32_16x16x32_bf16 v[24:27], v[206:209], v[178:181], v[24:27]
	v_mfma_f32_16x16x32_bf16 v[16:19], v[214:217], v[178:181], v[16:19]
	v_mfma_f32_16x16x32_bf16 v[8:11], v[206:209], v[186:189], v[8:11]
	v_mfma_f32_16x16x32_bf16 v[0:3], v[214:217], v[186:189], v[0:3]
	s_setprio 0
	s_add_i32 s41, s41, 2
	s_add_u32 s39, s39, 0x100
	s_addc_u32 s40, s40, 0
	s_add_u32 s18, s18, 0x100
	s_addc_u32 s19, s19, 0
	s_cmp_gt_u32 s41, 13
	s_barrier
	s_cbranch_scc0 .LBB0_2804
	v_mov_b32_e32 v139, v252
	s_lshl_b32 s11, s16, 8
	v_readfirstlane_b32 s9, v139
	s_ashr_i32 s16, s9, 2
	s_andn2_b32 s16, s16, 63
	s_lshr_b32 s9, s9, 1
	s_add_i32 s16, s16, s11
	s_lshl_b32 s11, s37, 7
	s_and_b32 s9, s9, 0x60
	v_and_or_b32 v138, v139, 15, s16
	s_or_b32 s9, s9, s11
	v_lshrrev_b32_e32 v139, 1, v139
	v_and_or_b32 v148, v139, 24, s9
	v_ashrrev_i32_e32 v139, 31, v138
	v_lshl_add_u64 v[140:141], v[138:139], 2, s[6:7]
	v_or_b32_e32 v146, 16, v138
	v_ashrrev_i32_e32 v147, 31, v146
	v_lshl_add_u64 v[142:143], v[146:147], 2, s[6:7]
	v_or_b32_e32 v144, 32, v138
	v_ashrrev_i32_e32 v145, 31, v144
	v_lshl_add_u64 v[142:143], v[144:145], 2, s[6:7]
	v_or_b32_e32 v142, 48, v138
	v_ashrrev_i32_e32 v143, 31, v142
	v_lshl_add_u64 v[154:155], v[142:143], 2, s[6:7]
	v_pk_mul_f32 v[120:121], v[124:125], v[120:121]
	v_pk_mul_f32 v[122:123], v[126:127], v[122:123]
	v_pk_mul_f32 v[112:113], v[116:117], v[112:113]
	v_pk_mul_f32 v[114:115], v[118:119], v[114:115]
	v_ashrrev_i32_e32 v149, 31, v148
	s_movk_i32 s9, 0x1600
	v_pk_mul_f32 v[104:105], v[108:109], v[104:105]
	v_pk_mul_f32 v[106:107], v[110:111], v[106:107]
	v_pk_mul_f32 v[96:97], v[100:101], v[96:97]
	v_pk_mul_f32 v[98:99], v[102:103], v[98:99]
	v_pk_mul_f32 v[88:89], v[92:93], v[88:89]
	v_pk_mul_f32 v[90:91], v[94:95], v[90:91]
	v_pk_mul_f32 v[80:81], v[84:85], v[80:81]
	v_pk_mul_f32 v[82:83], v[86:87], v[82:83]
	v_pk_mul_f32 v[72:73], v[76:77], v[72:73]
	v_pk_mul_f32 v[74:75], v[78:79], v[74:75]
	v_pk_mul_f32 v[64:65], v[68:69], v[64:65]
	v_pk_mul_f32 v[66:67], v[70:71], v[66:67]
	v_pk_mul_f32 v[56:57], v[60:61], v[56:57]
	v_pk_mul_f32 v[58:59], v[62:63], v[58:59]
	v_pk_mul_f32 v[48:49], v[52:53], v[48:49]
	v_pk_mul_f32 v[50:51], v[54:55], v[50:51]
	v_pk_mul_f32 v[40:41], v[44:45], v[40:41]
	v_pk_mul_f32 v[42:43], v[46:47], v[42:43]
	v_pk_mul_f32 v[32:33], v[36:37], v[32:33]
	v_pk_mul_f32 v[34:35], v[38:39], v[34:35]
	v_pk_mul_f32 v[24:25], v[28:29], v[24:25]
	v_pk_mul_f32 v[26:27], v[30:31], v[26:27]
	v_pk_mul_f32 v[16:17], v[20:21], v[16:17]
	v_pk_mul_f32 v[18:19], v[22:23], v[18:19]
	v_pk_mul_f32 v[8:9], v[12:13], v[8:9]
	v_pk_mul_f32 v[10:11], v[14:15], v[10:11]
	v_pk_mul_f32 v[0:1], v[4:5], v[0:1]
	v_pk_mul_f32 v[2:3], v[6:7], v[2:3]
	s_mov_b32 s37, s10
	s_mov_b32 s16, s8
	s_mov_b64 s[20:21], s[12:13]
	v_fmamk_f32 v143, v231, 0x3a800000, v194
	v_cmp_gt_f32_e32 vcc, s2, v143
	v_mul_f32_e32 v150, 0x4b800000, v143
	s_nop 0
	v_cndmask_b32_e32 v143, v143, v150, vcc
	v_rsq_f32_e32 v143, v143
	s_nop 0
	v_mul_f32_e32 v150, 0x45800000, v143
	v_cndmask_b32_e32 v143, v143, v150, vcc
	v_mul_f32_e32 v154, 0xbfb8aa3b, v143
	v_pk_mul_f32 v[158:159], v[124:125], v[154:155] op_sel_hi:[1,0]
	v_mul_f32_e32 v150, v143, v143
	v_exp_f32_e32 v143, v158
	v_pk_mul_f32 v[156:157], v[126:127], v[154:155] op_sel_hi:[1,0]
	v_add_f32_e32 v143, 1.0, v143
	v_rcp_f32_e32 v158, v143
	v_exp_f32_e32 v143, v159
	s_nop 0
	v_add_f32_e32 v143, 1.0, v143
	v_rcp_f32_e32 v159, v143
	v_exp_f32_e32 v143, v156
	v_pk_mul_f32 v[124:125], v[150:151], v[158:159] op_sel_hi:[0,1]
	v_add_f32_e32 v143, 1.0, v143
	v_rcp_f32_e32 v156, v143
	v_exp_f32_e32 v143, v157
	v_pk_mul_f32 v[120:121], v[120:121], v[124:125]
	v_add_f32_e32 v143, 1.0, v143
	v_rcp_f32_e32 v157, v143
	v_cvt_pk_bf16_f32 v124, v121, s0
	v_cvt_pk_bf16_f32 v120, v120, s0
	v_pk_mul_f32 v[126:127], v[150:151], v[156:157] op_sel_hi:[0,1]
	v_pk_mul_f32 v[122:123], v[122:123], v[126:127]
	s_nop 0
	v_cvt_pk_bf16_f32 v121, v122, v123
	v_lshlrev_b32_e32 v122, 16, v124
	v_pk_mul_f32 v[124:125], v[116:117], v[154:155] op_sel_hi:[1,0]
	v_or_b32_sdwa v120, v122, v120 dst_sel:DWORD dst_unused:UNUSED_PAD src0_sel:DWORD src1_sel:WORD_0
	v_pk_mul_f32 v[122:123], v[118:119], v[154:155] op_sel_hi:[1,0]
	v_exp_f32_e32 v124, v124
	v_exp_f32_e32 v125, v125
	v_exp_f32_e32 v122, v122
	v_exp_f32_e32 v123, v123
	v_add_f32_e32 v124, 1.0, v124
	v_add_f32_e32 v125, 1.0, v125
	v_rcp_f32_e32 v124, v124
	v_rcp_f32_e32 v125, v125
	v_add_f32_e32 v122, 1.0, v122
	v_add_f32_e32 v123, 1.0, v123
	v_rcp_f32_e32 v122, v122
	v_rcp_f32_e32 v123, v123
	v_pk_mul_f32 v[116:117], v[150:151], v[124:125] op_sel_hi:[0,1]
	v_pk_mul_f32 v[112:113], v[112:113], v[116:117]
	v_pk_mul_f32 v[118:119], v[150:151], v[122:123] op_sel_hi:[0,1]
	v_pk_mul_f32 v[114:115], v[114:115], v[118:119]
	v_cvt_pk_bf16_f32 v122, v112, v113
	v_mov_b64_e32 v[112:113], s[4:5]
	v_cvt_pk_bf16_f32 v123, v114, v115
	v_mad_i64_i32 v[116:117], s[18:19], v138, s9, v[112:113]
	v_lshlrev_b64 v[114:115], 1, v[148:149]
	v_lshl_add_u64 v[116:117], v[116:117], 0, v[114:115]
	global_store_dwordx4 v[116:117], v[120:123], off
	v_fmamk_f32 v116, v232, 0x3a800000, v194
	v_cmp_gt_f32_e32 vcc, s2, v116
	v_mul_f32_e32 v117, 0x4b800000, v116
	s_nop 0
	v_cndmask_b32_e32 v116, v116, v117, vcc
	v_rsq_f32_e32 v116, v116
	s_nop 0
	v_mul_f32_e32 v117, 0x45800000, v116
	v_cndmask_b32_e32 v116, v116, v117, vcc
	v_mul_f32_e32 v118, 0xbfb8aa3b, v116
	v_pk_mul_f32 v[122:123], v[108:109], v[118:119] op_sel_hi:[1,0]
	v_pk_mul_f32 v[120:121], v[110:111], v[118:119] op_sel_hi:[1,0]
	v_exp_f32_e32 v117, v122
	v_mul_f32_e32 v116, v116, v116
	v_add_f32_e32 v117, 1.0, v117
	v_rcp_f32_e32 v122, v117
	v_exp_f32_e32 v117, v123
	s_nop 0
	v_add_f32_e32 v117, 1.0, v117
	v_rcp_f32_e32 v123, v117
	v_exp_f32_e32 v117, v120
	s_nop 0
	v_add_f32_e32 v117, 1.0, v117
	v_rcp_f32_e32 v120, v117
	v_exp_f32_e32 v117, v121
	s_nop 0
	v_add_f32_e32 v117, 1.0, v117
	v_rcp_f32_e32 v121, v117
	v_pk_mul_f32 v[108:109], v[116:117], v[122:123] op_sel_hi:[0,1]
	v_pk_mul_f32 v[104:105], v[104:105], v[108:109]
	v_pk_mul_f32 v[110:111], v[116:117], v[120:121] op_sel_hi:[0,1]
	v_pk_mul_f32 v[106:107], v[106:107], v[110:111]
	v_cvt_pk_bf16_f32 v108, v105, s0
	v_cvt_pk_bf16_f32 v104, v104, s0
	v_cvt_pk_bf16_f32 v105, v106, v107
	v_lshlrev_b32_e32 v106, 16, v108
	v_pk_mul_f32 v[108:109], v[100:101], v[118:119] op_sel_hi:[1,0]
	v_or_b32_sdwa v104, v106, v104 dst_sel:DWORD dst_unused:UNUSED_PAD src0_sel:DWORD src1_sel:WORD_0
	v_pk_mul_f32 v[106:107], v[102:103], v[118:119] op_sel_hi:[1,0]
	v_exp_f32_e32 v108, v108
	v_exp_f32_e32 v109, v109
	v_exp_f32_e32 v106, v106
	v_exp_f32_e32 v107, v107
	v_add_f32_e32 v108, 1.0, v108
	v_add_f32_e32 v109, 1.0, v109
	v_rcp_f32_e32 v108, v108
	v_rcp_f32_e32 v109, v109
	v_add_f32_e32 v106, 1.0, v106
	v_add_f32_e32 v107, 1.0, v107
	v_rcp_f32_e32 v106, v106
	v_rcp_f32_e32 v107, v107
	v_pk_mul_f32 v[100:101], v[116:117], v[108:109] op_sel_hi:[0,1]
	v_pk_mul_f32 v[96:97], v[96:97], v[100:101]
	v_pk_mul_f32 v[102:103], v[116:117], v[106:107] op_sel_hi:[0,1]
	v_pk_mul_f32 v[98:99], v[98:99], v[102:103]
	v_cvt_pk_bf16_f32 v106, v96, v97
	v_mad_i64_i32 v[96:97], s[18:19], v146, s9, v[112:113]
	v_cvt_pk_bf16_f32 v107, v98, v99
	v_lshl_add_u64 v[96:97], v[96:97], 0, v[114:115]
	global_store_dwordx4 v[96:97], v[104:107], off
	v_fmamk_f32 v96, v233, 0x3a800000, v194
	v_cmp_gt_f32_e32 vcc, s2, v96
	v_mul_f32_e32 v97, 0x4b800000, v96
	s_nop 0
	v_cndmask_b32_e32 v96, v96, v97, vcc
	v_rsq_f32_e32 v96, v96
	s_nop 0
	v_mul_f32_e32 v97, 0x45800000, v96
	v_cndmask_b32_e32 v97, v96, v97, vcc
	v_mul_f32_e32 v96, 0xbfb8aa3b, v97
	v_pk_mul_f32 v[102:103], v[92:93], v[96:97] op_sel_hi:[1,0]
	v_mul_f32_e32 v98, v97, v97
	v_pk_mul_f32 v[100:101], v[94:95], v[96:97] op_sel_hi:[1,0]
	v_exp_f32_e32 v97, v102
	s_nop 0
	v_add_f32_e32 v97, 1.0, v97
	v_rcp_f32_e32 v102, v97
	v_exp_f32_e32 v97, v103
	s_nop 0
	v_add_f32_e32 v97, 1.0, v97
	v_rcp_f32_e32 v103, v97
	v_exp_f32_e32 v97, v100
	v_pk_mul_f32 v[92:93], v[98:99], v[102:103] op_sel_hi:[0,1]
	v_add_f32_e32 v97, 1.0, v97
	v_rcp_f32_e32 v100, v97
	v_exp_f32_e32 v97, v101
	v_pk_mul_f32 v[88:89], v[88:89], v[92:93]
	v_add_f32_e32 v97, 1.0, v97
	v_rcp_f32_e32 v101, v97
	v_cvt_pk_bf16_f32 v92, v89, s0
	v_cvt_pk_bf16_f32 v88, v88, s0
	v_pk_mul_f32 v[94:95], v[98:99], v[100:101] op_sel_hi:[0,1]
	v_pk_mul_f32 v[90:91], v[90:91], v[94:95]
	s_nop 0
	v_cvt_pk_bf16_f32 v89, v90, v91
	v_lshlrev_b32_e32 v90, 16, v92
	v_pk_mul_f32 v[92:93], v[84:85], v[96:97] op_sel_hi:[1,0]
	v_or_b32_sdwa v88, v90, v88 dst_sel:DWORD dst_unused:UNUSED_PAD src0_sel:DWORD src1_sel:WORD_0
	v_pk_mul_f32 v[90:91], v[86:87], v[96:97] op_sel_hi:[1,0]
	v_exp_f32_e32 v92, v92
	v_exp_f32_e32 v93, v93
	v_exp_f32_e32 v90, v90
	v_exp_f32_e32 v91, v91
	v_add_f32_e32 v92, 1.0, v92
	v_add_f32_e32 v93, 1.0, v93
	v_rcp_f32_e32 v92, v92
	v_rcp_f32_e32 v93, v93
	v_add_f32_e32 v90, 1.0, v90
	v_add_f32_e32 v91, 1.0, v91
	v_rcp_f32_e32 v90, v90
	v_rcp_f32_e32 v91, v91
	v_pk_mul_f32 v[84:85], v[98:99], v[92:93] op_sel_hi:[0,1]
	v_pk_mul_f32 v[80:81], v[80:81], v[84:85]
	v_pk_mul_f32 v[86:87], v[98:99], v[90:91] op_sel_hi:[0,1]
	v_pk_mul_f32 v[82:83], v[82:83], v[86:87]
	v_cvt_pk_bf16_f32 v90, v80, v81
	v_mad_i64_i32 v[80:81], s[18:19], v144, s9, v[112:113]
	v_cvt_pk_bf16_f32 v91, v82, v83
	v_lshl_add_u64 v[80:81], v[80:81], 0, v[114:115]
	global_store_dwordx4 v[80:81], v[88:91], off
	v_fmamk_f32 v80, v234, 0x3a800000, v194
	v_cmp_gt_f32_e32 vcc, s2, v80
	v_mul_f32_e32 v81, 0x4b800000, v80
	s_nop 0
	v_cndmask_b32_e32 v80, v80, v81, vcc
	v_rsq_f32_e32 v80, v80
	s_nop 0
	v_mul_f32_e32 v81, 0x45800000, v80
	v_cndmask_b32_e32 v81, v80, v81, vcc
	v_mul_f32_e32 v80, 0xbfb8aa3b, v81
	v_pk_mul_f32 v[86:87], v[76:77], v[80:81] op_sel_hi:[1,0]
	v_mul_f32_e32 v82, v81, v81
	v_pk_mul_f32 v[84:85], v[78:79], v[80:81] op_sel_hi:[1,0]
	v_exp_f32_e32 v81, v86
	s_nop 0
	v_add_f32_e32 v81, 1.0, v81
	v_rcp_f32_e32 v86, v81
	v_exp_f32_e32 v81, v87
	s_nop 0
	v_add_f32_e32 v81, 1.0, v81
	v_rcp_f32_e32 v87, v81
	v_exp_f32_e32 v81, v84
	v_pk_mul_f32 v[76:77], v[82:83], v[86:87] op_sel_hi:[0,1]
	v_add_f32_e32 v81, 1.0, v81
	v_rcp_f32_e32 v84, v81
	v_exp_f32_e32 v81, v85
	v_pk_mul_f32 v[72:73], v[72:73], v[76:77]
	v_add_f32_e32 v81, 1.0, v81
	v_rcp_f32_e32 v85, v81
	v_cvt_pk_bf16_f32 v76, v73, s0
	v_cvt_pk_bf16_f32 v72, v72, s0
	v_pk_mul_f32 v[78:79], v[82:83], v[84:85] op_sel_hi:[0,1]
	v_pk_mul_f32 v[74:75], v[74:75], v[78:79]
	s_nop 0
	v_cvt_pk_bf16_f32 v73, v74, v75
	v_lshlrev_b32_e32 v74, 16, v76
	v_pk_mul_f32 v[76:77], v[68:69], v[80:81] op_sel_hi:[1,0]
	v_or_b32_sdwa v72, v74, v72 dst_sel:DWORD dst_unused:UNUSED_PAD src0_sel:DWORD src1_sel:WORD_0
	v_pk_mul_f32 v[74:75], v[70:71], v[80:81] op_sel_hi:[1,0]
	v_exp_f32_e32 v76, v76
	v_exp_f32_e32 v77, v77
	v_exp_f32_e32 v74, v74
	v_exp_f32_e32 v75, v75
	v_add_f32_e32 v76, 1.0, v76
	v_add_f32_e32 v77, 1.0, v77
	v_rcp_f32_e32 v76, v76
	v_rcp_f32_e32 v77, v77
	v_add_f32_e32 v74, 1.0, v74
	v_add_f32_e32 v75, 1.0, v75
	v_rcp_f32_e32 v74, v74
	v_rcp_f32_e32 v75, v75
	v_pk_mul_f32 v[68:69], v[82:83], v[76:77] op_sel_hi:[0,1]
	v_pk_mul_f32 v[64:65], v[64:65], v[68:69]
	v_add_u32_e32 v69, 0x90, v138
	v_pk_mul_f32 v[70:71], v[82:83], v[74:75] op_sel_hi:[0,1]
	v_pk_mul_f32 v[66:67], v[66:67], v[70:71]
	v_cvt_pk_bf16_f32 v74, v64, v65
	v_mad_i64_i32 v[64:65], s[18:19], v142, s9, v[112:113]
	v_cvt_pk_bf16_f32 v75, v66, v67
	v_lshl_add_u64 v[64:65], v[64:65], 0, v[114:115]
	global_store_dwordx4 v[64:65], v[72:75], off
	v_add_u32_e32 v67, 0x80, v138
	v_add_u32_e32 v66, 0xa0, v138
	v_add_u32_e32 v64, 0xb0, v138
	v_fmamk_f32 v68, v235, 0x3a800000, v194
	v_cmp_gt_f32_e32 vcc, s2, v68
	v_mul_f32_e32 v70, 0x4b800000, v68
	s_nop 0
	v_cndmask_b32_e32 v68, v68, v70, vcc
	v_rsq_f32_e32 v68, v68
	s_nop 0
	v_mul_f32_e32 v70, 0x45800000, v68
	v_cndmask_b32_e32 v70, v68, v70, vcc
	v_mul_f32_e32 v68, 0xbfb8aa3b, v70
	v_pk_mul_f32 v[74:75], v[60:61], v[68:69] op_sel_hi:[1,0]
	v_pk_mul_f32 v[72:73], v[62:63], v[68:69] op_sel_hi:[1,0]
	v_exp_f32_e32 v74, v74
	v_exp_f32_e32 v75, v75
	v_exp_f32_e32 v72, v72
	v_exp_f32_e32 v73, v73
	v_add_f32_e32 v74, 1.0, v74
	v_add_f32_e32 v75, 1.0, v75
	v_rcp_f32_e32 v74, v74
	v_rcp_f32_e32 v75, v75
	v_add_f32_e32 v72, 1.0, v72
	v_add_f32_e32 v73, 1.0, v73
	v_rcp_f32_e32 v72, v72
	v_rcp_f32_e32 v73, v73
	v_mul_f32_e32 v70, v70, v70
	v_pk_mul_f32 v[60:61], v[70:71], v[74:75] op_sel_hi:[0,1]
	v_pk_mul_f32 v[56:57], v[56:57], v[60:61]
	v_pk_mul_f32 v[62:63], v[70:71], v[72:73] op_sel_hi:[0,1]
	v_pk_mul_f32 v[58:59], v[58:59], v[62:63]
	v_cvt_pk_bf16_f32 v60, v57, s0
	v_cvt_pk_bf16_f32 v56, v56, s0
	v_cvt_pk_bf16_f32 v57, v58, v59
	v_lshlrev_b32_e32 v58, 16, v60
	v_pk_mul_f32 v[60:61], v[52:53], v[68:69] op_sel_hi:[1,0]
	v_or_b32_sdwa v56, v58, v56 dst_sel:DWORD dst_unused:UNUSED_PAD src0_sel:DWORD src1_sel:WORD_0
	v_pk_mul_f32 v[58:59], v[54:55], v[68:69] op_sel_hi:[1,0]
	v_exp_f32_e32 v60, v60
	v_exp_f32_e32 v61, v61
	v_exp_f32_e32 v58, v58
	v_exp_f32_e32 v59, v59
	v_add_f32_e32 v60, 1.0, v60
	v_add_f32_e32 v61, 1.0, v61
	v_rcp_f32_e32 v60, v60
	v_rcp_f32_e32 v61, v61
	v_add_f32_e32 v58, 1.0, v58
	v_add_f32_e32 v59, 1.0, v59
	v_rcp_f32_e32 v58, v58
	v_rcp_f32_e32 v59, v59
	v_pk_mul_f32 v[52:53], v[70:71], v[60:61] op_sel_hi:[0,1]
	v_pk_mul_f32 v[48:49], v[48:49], v[52:53]
	v_pk_mul_f32 v[54:55], v[70:71], v[58:59] op_sel_hi:[0,1]
	v_pk_mul_f32 v[50:51], v[50:51], v[54:55]
	v_cvt_pk_bf16_f32 v58, v48, v49
	v_mad_i64_i32 v[48:49], s[18:19], v67, s9, v[112:113]
	v_cvt_pk_bf16_f32 v59, v50, v51
	v_lshl_add_u64 v[48:49], v[48:49], 0, v[114:115]
	global_store_dwordx4 v[48:49], v[56:59], off
	v_fmamk_f32 v48, v236, 0x3a800000, v194
	v_cmp_gt_f32_e32 vcc, s2, v48
	v_mul_f32_e32 v49, 0x4b800000, v48
	s_nop 0
	v_cndmask_b32_e32 v48, v48, v49, vcc
	v_rsq_f32_e32 v48, v48
	s_nop 0
	v_mul_f32_e32 v49, 0x45800000, v48
	v_cndmask_b32_e32 v49, v48, v49, vcc
	v_mul_f32_e32 v48, 0xbfb8aa3b, v49
	v_pk_mul_f32 v[54:55], v[44:45], v[48:49] op_sel_hi:[1,0]
	v_mul_f32_e32 v50, v49, v49
	v_pk_mul_f32 v[52:53], v[46:47], v[48:49] op_sel_hi:[1,0]
	v_exp_f32_e32 v49, v54
	s_nop 0
	v_add_f32_e32 v49, 1.0, v49
	v_rcp_f32_e32 v54, v49
	v_exp_f32_e32 v49, v55
	s_nop 0
	v_add_f32_e32 v49, 1.0, v49
	v_rcp_f32_e32 v55, v49
	v_exp_f32_e32 v49, v52
	v_pk_mul_f32 v[44:45], v[50:51], v[54:55] op_sel_hi:[0,1]
	v_add_f32_e32 v49, 1.0, v49
	v_rcp_f32_e32 v52, v49
	v_exp_f32_e32 v49, v53
	v_pk_mul_f32 v[40:41], v[40:41], v[44:45]
	v_add_f32_e32 v49, 1.0, v49
	v_rcp_f32_e32 v53, v49
	v_cvt_pk_bf16_f32 v44, v41, s0
	v_cvt_pk_bf16_f32 v40, v40, s0
	v_pk_mul_f32 v[46:47], v[50:51], v[52:53] op_sel_hi:[0,1]
	v_pk_mul_f32 v[42:43], v[42:43], v[46:47]
	s_nop 0
	v_cvt_pk_bf16_f32 v41, v42, v43
	v_lshlrev_b32_e32 v42, 16, v44
	v_pk_mul_f32 v[44:45], v[36:37], v[48:49] op_sel_hi:[1,0]
	v_or_b32_sdwa v40, v42, v40 dst_sel:DWORD dst_unused:UNUSED_PAD src0_sel:DWORD src1_sel:WORD_0
	v_pk_mul_f32 v[42:43], v[38:39], v[48:49] op_sel_hi:[1,0]
	v_exp_f32_e32 v44, v44
	v_exp_f32_e32 v45, v45
	v_exp_f32_e32 v42, v42
	v_exp_f32_e32 v43, v43
	v_add_f32_e32 v44, 1.0, v44
	v_add_f32_e32 v45, 1.0, v45
	v_rcp_f32_e32 v44, v44
	v_rcp_f32_e32 v45, v45
	v_add_f32_e32 v42, 1.0, v42
	v_add_f32_e32 v43, 1.0, v43
	v_rcp_f32_e32 v42, v42
	v_rcp_f32_e32 v43, v43
	v_pk_mul_f32 v[36:37], v[50:51], v[44:45] op_sel_hi:[0,1]
	v_pk_mul_f32 v[32:33], v[32:33], v[36:37]
	v_pk_mul_f32 v[38:39], v[50:51], v[42:43] op_sel_hi:[0,1]
	v_pk_mul_f32 v[34:35], v[34:35], v[38:39]
	v_cvt_pk_bf16_f32 v42, v32, v33
	v_mad_i64_i32 v[32:33], s[18:19], v69, s9, v[112:113]
	v_cvt_pk_bf16_f32 v43, v34, v35
	v_lshl_add_u64 v[32:33], v[32:33], 0, v[114:115]
	global_store_dwordx4 v[32:33], v[40:43], off
	v_fmamk_f32 v32, v237, 0x3a800000, v194
	v_cmp_gt_f32_e32 vcc, s2, v32
	v_mul_f32_e32 v33, 0x4b800000, v32
	s_nop 0
	v_cndmask_b32_e32 v32, v32, v33, vcc
	v_rsq_f32_e32 v32, v32
	s_nop 0
	v_mul_f32_e32 v33, 0x45800000, v32
	v_cndmask_b32_e32 v33, v32, v33, vcc
	v_mul_f32_e32 v32, 0xbfb8aa3b, v33
	v_pk_mul_f32 v[38:39], v[28:29], v[32:33] op_sel_hi:[1,0]
	v_mul_f32_e32 v34, v33, v33
	v_pk_mul_f32 v[36:37], v[30:31], v[32:33] op_sel_hi:[1,0]
	v_exp_f32_e32 v33, v38
	s_nop 0
	v_add_f32_e32 v33, 1.0, v33
	v_rcp_f32_e32 v38, v33
	v_exp_f32_e32 v33, v39
	s_nop 0
	v_add_f32_e32 v33, 1.0, v33
	v_rcp_f32_e32 v39, v33
	v_exp_f32_e32 v33, v36
	v_pk_mul_f32 v[28:29], v[34:35], v[38:39] op_sel_hi:[0,1]
	v_add_f32_e32 v33, 1.0, v33
	v_rcp_f32_e32 v36, v33
	v_exp_f32_e32 v33, v37
	v_pk_mul_f32 v[24:25], v[24:25], v[28:29]
	v_add_f32_e32 v33, 1.0, v33
	v_rcp_f32_e32 v37, v33
	v_cvt_pk_bf16_f32 v28, v25, s0
	v_cvt_pk_bf16_f32 v24, v24, s0
	v_pk_mul_f32 v[30:31], v[34:35], v[36:37] op_sel_hi:[0,1]
	v_pk_mul_f32 v[26:27], v[26:27], v[30:31]
	s_nop 0
	v_cvt_pk_bf16_f32 v25, v26, v27
	v_lshlrev_b32_e32 v26, 16, v28
	v_pk_mul_f32 v[28:29], v[20:21], v[32:33] op_sel_hi:[1,0]
	v_or_b32_sdwa v24, v26, v24 dst_sel:DWORD dst_unused:UNUSED_PAD src0_sel:DWORD src1_sel:WORD_0
	v_pk_mul_f32 v[26:27], v[22:23], v[32:33] op_sel_hi:[1,0]
	v_exp_f32_e32 v28, v28
	v_exp_f32_e32 v29, v29
	v_exp_f32_e32 v26, v26
	v_exp_f32_e32 v27, v27
	v_add_f32_e32 v28, 1.0, v28
	v_add_f32_e32 v29, 1.0, v29
	v_rcp_f32_e32 v28, v28
	v_rcp_f32_e32 v29, v29
	v_add_f32_e32 v26, 1.0, v26
	v_add_f32_e32 v27, 1.0, v27
	v_rcp_f32_e32 v26, v26
	v_rcp_f32_e32 v27, v27
	v_pk_mul_f32 v[20:21], v[34:35], v[28:29] op_sel_hi:[0,1]
	v_pk_mul_f32 v[16:17], v[16:17], v[20:21]
	v_pk_mul_f32 v[22:23], v[34:35], v[26:27] op_sel_hi:[0,1]
	v_pk_mul_f32 v[18:19], v[18:19], v[22:23]
	v_cvt_pk_bf16_f32 v26, v16, v17
	v_mad_i64_i32 v[16:17], s[18:19], v66, s9, v[112:113]
	v_cvt_pk_bf16_f32 v27, v18, v19
	v_lshl_add_u64 v[16:17], v[16:17], 0, v[114:115]
	global_store_dwordx4 v[16:17], v[24:27], off
	v_fmamk_f32 v16, v238, 0x3a800000, v194
	v_cmp_gt_f32_e32 vcc, s2, v16
	v_mul_f32_e32 v17, 0x4b800000, v16
	s_nop 0
	v_cndmask_b32_e32 v16, v16, v17, vcc
	v_rsq_f32_e32 v16, v16
	s_nop 0
	v_mul_f32_e32 v17, 0x45800000, v16
	v_cndmask_b32_e32 v17, v16, v17, vcc
	v_mul_f32_e32 v16, 0xbfb8aa3b, v17
	v_pk_mul_f32 v[22:23], v[12:13], v[16:17] op_sel_hi:[1,0]
	v_mul_f32_e32 v18, v17, v17
	v_pk_mul_f32 v[20:21], v[14:15], v[16:17] op_sel_hi:[1,0]
	v_exp_f32_e32 v17, v22
	s_and_b64 vcc, exec, s[0:1]
	v_add_f32_e32 v17, 1.0, v17
	v_rcp_f32_e32 v22, v17
	v_exp_f32_e32 v17, v23
	s_nop 0
	v_add_f32_e32 v17, 1.0, v17
	v_rcp_f32_e32 v23, v17
	v_exp_f32_e32 v17, v20
	v_pk_mul_f32 v[12:13], v[18:19], v[22:23] op_sel_hi:[0,1]
	v_add_f32_e32 v17, 1.0, v17
	v_rcp_f32_e32 v20, v17
	v_exp_f32_e32 v17, v21
	v_pk_mul_f32 v[8:9], v[8:9], v[12:13]
	v_add_f32_e32 v17, 1.0, v17
	v_rcp_f32_e32 v21, v17
	v_cvt_pk_bf16_f32 v12, v9, s0
	v_cvt_pk_bf16_f32 v8, v8, s0
	v_pk_mul_f32 v[14:15], v[18:19], v[20:21] op_sel_hi:[0,1]
	v_pk_mul_f32 v[10:11], v[10:11], v[14:15]
	s_nop 0
	v_cvt_pk_bf16_f32 v9, v10, v11
	v_lshlrev_b32_e32 v10, 16, v12
	v_pk_mul_f32 v[12:13], v[4:5], v[16:17] op_sel_hi:[1,0]
	v_or_b32_sdwa v8, v10, v8 dst_sel:DWORD dst_unused:UNUSED_PAD src0_sel:DWORD src1_sel:WORD_0
	v_pk_mul_f32 v[10:11], v[6:7], v[16:17] op_sel_hi:[1,0]
	v_exp_f32_e32 v12, v12
	v_exp_f32_e32 v13, v13
	v_exp_f32_e32 v10, v10
	v_exp_f32_e32 v11, v11
	v_add_f32_e32 v12, 1.0, v12
	v_add_f32_e32 v13, 1.0, v13
	v_rcp_f32_e32 v12, v12
	v_rcp_f32_e32 v13, v13
	v_add_f32_e32 v10, 1.0, v10
	v_add_f32_e32 v11, 1.0, v11
	v_rcp_f32_e32 v10, v10
	v_rcp_f32_e32 v11, v11
	v_pk_mul_f32 v[4:5], v[18:19], v[12:13] op_sel_hi:[0,1]
	v_pk_mul_f32 v[0:1], v[0:1], v[4:5]
	v_pk_mul_f32 v[6:7], v[18:19], v[10:11] op_sel_hi:[0,1]
	v_pk_mul_f32 v[2:3], v[2:3], v[6:7]
	v_cvt_pk_bf16_f32 v10, v0, v1
	v_mad_i64_i32 v[0:1], s[18:19], v64, s9, v[112:113]
	v_cvt_pk_bf16_f32 v11, v2, v3
	v_lshl_add_u64 v[0:1], v[0:1], 0, v[114:115]
	s_mov_b64 s[18:19], s[14:15]
	global_store_dwordx4 v[0:1], v[8:11], off
	s_cbranch_vccz .LBB0_2801
	s_waitcnt vmcnt(0)
	s_cmpk_gt_u32 s25, 0xff
	s_cbranch_scc1 .LBB0_2808
	s_barrier
